# GEMM K-loops: per A-row-fragment, the four column fragments' accumulators in turn, each with its two K-halves chained back to back (A operand pair reused across 8 MFMAs)
# speedup vs baseline: 1.0183x; 1.0079x over previous
.LBB0_260:
	v_add_u32_e32 v168, 0x10000, v232
	v_add_u32_e32 v180, 0x14000, v232
	v_lshl_add_u64 v[224:225], v[222:223], 0, s[62:63]
	s_add_i32 m0, s35, 0xc000
	s_waitcnt lgkmcnt(0)
	ds_read_b128 v[148:151], v207
	ds_read_b128 v[164:167], v207 offset:1024
	ds_read_b128 v[144:147], v207 offset:2048
	ds_read_b128 v[160:163], v207 offset:3072
	ds_read_b128 v[140:143], v207 offset:4096
	ds_read_b128 v[156:159], v207 offset:5120
	ds_read_b128 v[136:139], v207 offset:6144
	ds_read_b128 v[152:155], v207 offset:7168
	ds_read_b128 v[184:187], v168
	ds_read_b128 v[188:191], v168 offset:1024
	ds_read_b128 v[192:195], v168 offset:2048
	ds_read_b128 v[196:199], v168 offset:3072
	ds_read_b128 v[168:171], v180
	ds_read_b128 v[172:175], v180 offset:1024
	ds_read_b128 v[176:179], v180 offset:2048
	ds_read_b128 v[180:183], v180 offset:3072
	global_load_lds_dwordx4 v[224:225], off
	v_lshl_add_u64 v[224:225], v[220:221], 0, s[62:63]
	s_add_i32 m0, s35, 0xe000
	s_nop 0
	global_load_lds_dwordx4 v[224:225], off
	s_waitcnt vmcnt(8)
	s_waitcnt lgkmcnt(0)
	s_barrier
	s_setprio 1
	s_waitcnt lgkmcnt(0)
	v_mfma_f32_16x16x32_bf16 v[132:135], v[184:187], v[148:151], v[132:135]
	v_mfma_f32_16x16x32_bf16 v[132:135], v[188:191], v[164:167], v[132:135]
	v_mfma_f32_16x16x32_bf16 v[128:131], v[192:195], v[148:151], v[128:131]
	v_mfma_f32_16x16x32_bf16 v[128:131], v[196:199], v[164:167], v[128:131]
	v_mfma_f32_16x16x32_bf16 v[124:127], v[168:171], v[148:151], v[124:127]
	v_mfma_f32_16x16x32_bf16 v[124:127], v[172:175], v[164:167], v[124:127]
	v_mfma_f32_16x16x32_bf16 v[120:123], v[176:179], v[148:151], v[120:123]
	v_mfma_f32_16x16x32_bf16 v[120:123], v[180:183], v[164:167], v[120:123]
	v_mfma_f32_16x16x32_bf16 v[116:119], v[184:187], v[144:147], v[116:119]
	v_mfma_f32_16x16x32_bf16 v[116:119], v[188:191], v[160:163], v[116:119]
	v_mfma_f32_16x16x32_bf16 v[112:115], v[192:195], v[144:147], v[112:115]
	v_mfma_f32_16x16x32_bf16 v[112:115], v[196:199], v[160:163], v[112:115]
	v_mfma_f32_16x16x32_bf16 v[108:111], v[168:171], v[144:147], v[108:111]
	v_mfma_f32_16x16x32_bf16 v[108:111], v[172:175], v[160:163], v[108:111]
	v_mfma_f32_16x16x32_bf16 v[104:107], v[176:179], v[144:147], v[104:107]
	v_mfma_f32_16x16x32_bf16 v[104:107], v[180:183], v[160:163], v[104:107]
	s_setprio 0
	s_setprio 1
	v_mfma_f32_16x16x32_bf16 v[100:103], v[184:187], v[140:143], v[100:103]
	v_mfma_f32_16x16x32_bf16 v[100:103], v[188:191], v[156:159], v[100:103]
	v_mfma_f32_16x16x32_bf16 v[96:99], v[192:195], v[140:143], v[96:99]
	v_mfma_f32_16x16x32_bf16 v[96:99], v[196:199], v[156:159], v[96:99]
	v_mfma_f32_16x16x32_bf16 v[92:95], v[168:171], v[140:143], v[92:95]
	v_mfma_f32_16x16x32_bf16 v[92:95], v[172:175], v[156:159], v[92:95]
	v_mfma_f32_16x16x32_bf16 v[88:91], v[176:179], v[140:143], v[88:91]
	v_mfma_f32_16x16x32_bf16 v[88:91], v[180:183], v[156:159], v[88:91]
	v_mfma_f32_16x16x32_bf16 v[84:87], v[184:187], v[136:139], v[84:87]
	v_mfma_f32_16x16x32_bf16 v[84:87], v[188:191], v[152:155], v[84:87]
	v_mfma_f32_16x16x32_bf16 v[80:83], v[192:195], v[136:139], v[80:83]
	v_mfma_f32_16x16x32_bf16 v[80:83], v[196:199], v[152:155], v[80:83]
	v_mfma_f32_16x16x32_bf16 v[76:79], v[168:171], v[136:139], v[76:79]
	v_mfma_f32_16x16x32_bf16 v[76:79], v[172:175], v[152:155], v[76:79]
	v_mfma_f32_16x16x32_bf16 v[72:75], v[176:179], v[136:139], v[72:75]
	v_mfma_f32_16x16x32_bf16 v[72:75], v[180:183], v[152:155], v[72:75]
	s_setprio 0
	s_barrier
	v_cndmask_b32_e64 v204, 0, 1, s[60:61]
	v_cmp_ne_u32_e64 s[50:51], 1, v204
	s_andn2_b64 vcc, exec, s[60:61]
	s_cbranch_vccnz .LBB0_262
	ds_read_b128 v[148:151], v207 offset:16384
	ds_read_b128 v[164:167], v207 offset:17408
	ds_read_b128 v[144:147], v207 offset:18432
	ds_read_b128 v[160:163], v207 offset:19456
	ds_read_b128 v[140:143], v207 offset:20480
	ds_read_b128 v[156:159], v207 offset:21504
	ds_read_b128 v[136:139], v207 offset:22528
	ds_read_b128 v[152:155], v207 offset:23552
.LBB0_262:
	s_add_u32 s12, s58, s62
	s_addc_u32 s13, s59, s63
	s_add_u32 s14, s12, 0x100
	s_addc_u32 s15, s13, 0
	s_add_u32 s75, s26, s62
	s_addc_u32 s76, s27, s63
	s_cmpk_eq_i32 s62, 0xf00
	s_cselect_b64 s[52:53], -1, 0
	s_and_b64 s[12:13], s[52:53], exec
	s_cselect_b32 s13, s21, s76
	s_cselect_b32 s12, s73, s75
	s_mov_b32 m0, s38
	s_cselect_b32 s15, s25, s15
	s_cselect_b32 s14, s33, s14
	v_lshl_add_u64 v[224:225], s[12:13], 0, v[208:209]
	s_add_u32 s76, s12, 0x80000
	global_load_lds_dwordx4 v[224:225], off
	v_lshl_add_u64 v[226:227], s[12:13], 0, v[212:213]
	s_mov_b32 m0, s39
	s_addc_u32 s77, s13, 0
	global_load_lds_dwordx4 v[226:227], off
	v_lshl_add_u64 v[228:229], s[76:77], 0, v[208:209]
	s_mov_b32 m0, s40
	v_lshl_add_u64 v[230:231], s[14:15], 0, v[210:211]
	global_load_lds_dwordx4 v[228:229], off
	v_lshl_add_u64 v[228:229], s[76:77], 0, v[212:213]
	s_mov_b32 m0, s41
	s_and_b64 vcc, exec, s[50:51]
	global_load_lds_dwordx4 v[228:229], off
	v_lshl_add_u64 v[228:229], s[14:15], 0, v[4:5]
	s_mov_b32 m0, s35
	s_nop 0
	global_load_lds_dwordx4 v[228:229], off
	s_mov_b32 m0, s43
	s_nop 0
	global_load_lds_dwordx4 v[230:231], off
	s_waitcnt vmcnt(8)
	s_waitcnt lgkmcnt(0)
	s_barrier
	s_cbranch_vccnz .LBB0_264
	s_setprio 1
	s_waitcnt lgkmcnt(0)
	v_mfma_f32_16x16x32_bf16 v[68:71], v[184:187], v[148:151], v[68:71]
	v_mfma_f32_16x16x32_bf16 v[68:71], v[188:191], v[164:167], v[68:71]
	v_mfma_f32_16x16x32_bf16 v[64:67], v[192:195], v[148:151], v[64:67]
	v_mfma_f32_16x16x32_bf16 v[64:67], v[196:199], v[164:167], v[64:67]
	v_mfma_f32_16x16x32_bf16 v[60:63], v[168:171], v[148:151], v[60:63]
	v_mfma_f32_16x16x32_bf16 v[60:63], v[172:175], v[164:167], v[60:63]
	v_mfma_f32_16x16x32_bf16 v[56:59], v[176:179], v[148:151], v[56:59]
	v_mfma_f32_16x16x32_bf16 v[56:59], v[180:183], v[164:167], v[56:59]
	v_mfma_f32_16x16x32_bf16 v[52:55], v[184:187], v[144:147], v[52:55]
	v_mfma_f32_16x16x32_bf16 v[52:55], v[188:191], v[160:163], v[52:55]
	v_mfma_f32_16x16x32_bf16 v[48:51], v[192:195], v[144:147], v[48:51]
	v_mfma_f32_16x16x32_bf16 v[48:51], v[196:199], v[160:163], v[48:51]
	v_mfma_f32_16x16x32_bf16 v[44:47], v[168:171], v[144:147], v[44:47]
	v_mfma_f32_16x16x32_bf16 v[44:47], v[172:175], v[160:163], v[44:47]
	v_mfma_f32_16x16x32_bf16 v[40:43], v[176:179], v[144:147], v[40:43]
	v_mfma_f32_16x16x32_bf16 v[40:43], v[180:183], v[160:163], v[40:43]
	s_setprio 0
	s_setprio 1
	v_mfma_f32_16x16x32_bf16 v[36:39], v[184:187], v[140:143], v[36:39]
	v_mfma_f32_16x16x32_bf16 v[36:39], v[188:191], v[156:159], v[36:39]
	v_mfma_f32_16x16x32_bf16 v[32:35], v[192:195], v[140:143], v[32:35]
	v_mfma_f32_16x16x32_bf16 v[32:35], v[196:199], v[156:159], v[32:35]
	v_mfma_f32_16x16x32_bf16 v[28:31], v[168:171], v[140:143], v[28:31]
	v_mfma_f32_16x16x32_bf16 v[28:31], v[172:175], v[156:159], v[28:31]
	v_mfma_f32_16x16x32_bf16 v[24:27], v[176:179], v[140:143], v[24:27]
	v_mfma_f32_16x16x32_bf16 v[24:27], v[180:183], v[156:159], v[24:27]
	v_mfma_f32_16x16x32_bf16 v[20:23], v[184:187], v[136:139], v[20:23]
	v_mfma_f32_16x16x32_bf16 v[20:23], v[188:191], v[152:155], v[20:23]
	v_mfma_f32_16x16x32_bf16 v[16:19], v[192:195], v[136:139], v[16:19]
	v_mfma_f32_16x16x32_bf16 v[16:19], v[196:199], v[152:155], v[16:19]
	v_mfma_f32_16x16x32_bf16 v[12:15], v[168:171], v[136:139], v[12:15]
	v_mfma_f32_16x16x32_bf16 v[12:15], v[172:175], v[152:155], v[12:15]
	v_mfma_f32_16x16x32_bf16 v[8:11], v[176:179], v[136:139], v[8:11]
	v_mfma_f32_16x16x32_bf16 v[8:11], v[180:183], v[152:155], v[8:11]
	s_setprio 0
.LBB0_264:
	s_barrier
	v_cndmask_b32_e64 v241, v219, 0, s[52:53]
	v_cndmask_b32_e64 v240, v218, v2, s[52:53]
	v_lshl_add_u64 v[240:241], s[14:15], 0, v[240:241]
	s_mov_b32 m0, s45
	v_add_u32_e32 v168, 0x18000, v232
	v_add_u32_e32 v180, 0x1c000, v232
	v_lshl_add_u64 v[242:243], v[240:241], 0, v[4:5]
	s_waitcnt lgkmcnt(0)
	ds_read_b128 v[148:151], v207 offset:32768
	ds_read_b128 v[164:167], v207 offset:33792
	ds_read_b128 v[144:147], v207 offset:34816
	ds_read_b128 v[160:163], v207 offset:35840
	ds_read_b128 v[140:143], v207 offset:36864
	ds_read_b128 v[156:159], v207 offset:37888
	ds_read_b128 v[136:139], v207 offset:38912
	ds_read_b128 v[152:155], v207 offset:39936
	ds_read_b128 v[184:187], v168
	ds_read_b128 v[188:191], v168 offset:1024
	ds_read_b128 v[192:195], v168 offset:2048
	ds_read_b128 v[196:199], v168 offset:3072
	ds_read_b128 v[168:171], v180
	ds_read_b128 v[172:175], v180 offset:1024
	ds_read_b128 v[176:179], v180 offset:2048
	ds_read_b128 v[180:183], v180 offset:3072
	global_load_lds_dwordx4 v[242:243], off
	v_lshl_add_u64 v[240:241], v[240:241], 0, v[210:211]
	s_mov_b32 m0, s47
	s_nop 0
	global_load_lds_dwordx4 v[240:241], off
	s_waitcnt vmcnt(8)
	s_waitcnt lgkmcnt(0)
	s_barrier
	s_setprio 1
	s_waitcnt lgkmcnt(0)
	v_mfma_f32_16x16x32_bf16 v[132:135], v[184:187], v[148:151], v[132:135]
	v_mfma_f32_16x16x32_bf16 v[132:135], v[188:191], v[164:167], v[132:135]
	v_mfma_f32_16x16x32_bf16 v[128:131], v[192:195], v[148:151], v[128:131]
	v_mfma_f32_16x16x32_bf16 v[128:131], v[196:199], v[164:167], v[128:131]
	v_mfma_f32_16x16x32_bf16 v[124:127], v[168:171], v[148:151], v[124:127]
	v_mfma_f32_16x16x32_bf16 v[124:127], v[172:175], v[164:167], v[124:127]
	v_mfma_f32_16x16x32_bf16 v[120:123], v[176:179], v[148:151], v[120:123]
	v_mfma_f32_16x16x32_bf16 v[120:123], v[180:183], v[164:167], v[120:123]
	v_mfma_f32_16x16x32_bf16 v[116:119], v[184:187], v[144:147], v[116:119]
	v_mfma_f32_16x16x32_bf16 v[116:119], v[188:191], v[160:163], v[116:119]
	v_mfma_f32_16x16x32_bf16 v[112:115], v[192:195], v[144:147], v[112:115]
	v_mfma_f32_16x16x32_bf16 v[112:115], v[196:199], v[160:163], v[112:115]
	v_mfma_f32_16x16x32_bf16 v[108:111], v[168:171], v[144:147], v[108:111]
	v_mfma_f32_16x16x32_bf16 v[108:111], v[172:175], v[160:163], v[108:111]
	v_mfma_f32_16x16x32_bf16 v[104:107], v[176:179], v[144:147], v[104:107]
	v_mfma_f32_16x16x32_bf16 v[104:107], v[180:183], v[160:163], v[104:107]
	s_setprio 0
	s_setprio 1
	v_mfma_f32_16x16x32_bf16 v[100:103], v[184:187], v[140:143], v[100:103]
	v_mfma_f32_16x16x32_bf16 v[100:103], v[188:191], v[156:159], v[100:103]
	v_mfma_f32_16x16x32_bf16 v[96:99], v[192:195], v[140:143], v[96:99]
	v_mfma_f32_16x16x32_bf16 v[96:99], v[196:199], v[156:159], v[96:99]
	v_mfma_f32_16x16x32_bf16 v[92:95], v[168:171], v[140:143], v[92:95]
	v_mfma_f32_16x16x32_bf16 v[92:95], v[172:175], v[156:159], v[92:95]
	v_mfma_f32_16x16x32_bf16 v[88:91], v[176:179], v[140:143], v[88:91]
	v_mfma_f32_16x16x32_bf16 v[88:91], v[180:183], v[156:159], v[88:91]
	v_mfma_f32_16x16x32_bf16 v[84:87], v[184:187], v[136:139], v[84:87]
	v_mfma_f32_16x16x32_bf16 v[84:87], v[188:191], v[152:155], v[84:87]
	v_mfma_f32_16x16x32_bf16 v[80:83], v[192:195], v[136:139], v[80:83]
	v_mfma_f32_16x16x32_bf16 v[80:83], v[196:199], v[152:155], v[80:83]
	v_mfma_f32_16x16x32_bf16 v[76:79], v[168:171], v[136:139], v[76:79]
	v_mfma_f32_16x16x32_bf16 v[76:79], v[172:175], v[152:155], v[76:79]
	v_mfma_f32_16x16x32_bf16 v[72:75], v[176:179], v[136:139], v[72:75]
	v_mfma_f32_16x16x32_bf16 v[72:75], v[180:183], v[152:155], v[72:75]
	s_setprio 0
	s_barrier
	s_and_b64 vcc, exec, s[50:51]
	s_cbranch_vccnz .LBB0_266
	ds_read_b128 v[148:151], v207 offset:49152
	ds_read_b128 v[164:167], v207 offset:50176
	ds_read_b128 v[144:147], v207 offset:51200
	ds_read_b128 v[160:163], v207 offset:52224
	ds_read_b128 v[140:143], v207 offset:53248
	ds_read_b128 v[156:159], v207 offset:54272
	ds_read_b128 v[136:139], v207 offset:55296
	ds_read_b128 v[152:155], v207 offset:56320
.LBB0_266:
	s_mov_b32 m0, s64
	v_lshl_add_u64 v[224:225], v[224:225], 0, s[0:1]
	s_add_u32 s12, s12, 0x80080
	global_load_lds_dwordx4 v[224:225], off
	v_lshl_add_u64 v[224:225], v[226:227], 0, s[0:1]
	s_mov_b32 m0, s65
	s_addc_u32 s13, s13, 0
	global_load_lds_dwordx4 v[224:225], off
	v_lshl_add_u64 v[224:225], s[12:13], 0, v[208:209]
	s_mov_b32 m0, s68
	s_and_b64 vcc, exec, s[50:51]
	global_load_lds_dwordx4 v[224:225], off
	v_lshl_add_u64 v[224:225], s[12:13], 0, v[212:213]
	s_mov_b32 m0, s69
	s_nop 0
	global_load_lds_dwordx4 v[224:225], off
	v_lshl_add_u64 v[224:225], v[228:229], 0, s[0:1]
	s_mov_b32 m0, s66
	s_nop 0
	global_load_lds_dwordx4 v[224:225], off
	v_lshl_add_u64 v[224:225], v[230:231], 0, s[0:1]
	s_mov_b32 m0, s67
	s_nop 0
	global_load_lds_dwordx4 v[224:225], off
	s_waitcnt vmcnt(8)
	s_waitcnt lgkmcnt(0)
	s_barrier
	s_cbranch_vccnz .LBB0_259
	s_setprio 1
	s_waitcnt lgkmcnt(0)
	v_mfma_f32_16x16x32_bf16 v[68:71], v[184:187], v[148:151], v[68:71]
	v_mfma_f32_16x16x32_bf16 v[68:71], v[188:191], v[164:167], v[68:71]
	v_mfma_f32_16x16x32_bf16 v[64:67], v[192:195], v[148:151], v[64:67]
	v_mfma_f32_16x16x32_bf16 v[64:67], v[196:199], v[164:167], v[64:67]
	v_mfma_f32_16x16x32_bf16 v[60:63], v[168:171], v[148:151], v[60:63]
	v_mfma_f32_16x16x32_bf16 v[60:63], v[172:175], v[164:167], v[60:63]
	v_mfma_f32_16x16x32_bf16 v[56:59], v[176:179], v[148:151], v[56:59]
	v_mfma_f32_16x16x32_bf16 v[56:59], v[180:183], v[164:167], v[56:59]
	v_mfma_f32_16x16x32_bf16 v[52:55], v[184:187], v[144:147], v[52:55]
	v_mfma_f32_16x16x32_bf16 v[52:55], v[188:191], v[160:163], v[52:55]
	v_mfma_f32_16x16x32_bf16 v[48:51], v[192:195], v[144:147], v[48:51]
	v_mfma_f32_16x16x32_bf16 v[48:51], v[196:199], v[160:163], v[48:51]
	v_mfma_f32_16x16x32_bf16 v[44:47], v[168:171], v[144:147], v[44:47]
	v_mfma_f32_16x16x32_bf16 v[44:47], v[172:175], v[160:163], v[44:47]
	v_mfma_f32_16x16x32_bf16 v[40:43], v[176:179], v[144:147], v[40:43]
	v_mfma_f32_16x16x32_bf16 v[40:43], v[180:183], v[160:163], v[40:43]
	s_setprio 0
	s_setprio 1
	v_mfma_f32_16x16x32_bf16 v[36:39], v[184:187], v[140:143], v[36:39]
	v_mfma_f32_16x16x32_bf16 v[36:39], v[188:191], v[156:159], v[36:39]
	v_mfma_f32_16x16x32_bf16 v[32:35], v[192:195], v[140:143], v[32:35]
	v_mfma_f32_16x16x32_bf16 v[32:35], v[196:199], v[156:159], v[32:35]
	v_mfma_f32_16x16x32_bf16 v[28:31], v[168:171], v[140:143], v[28:31]
	v_mfma_f32_16x16x32_bf16 v[28:31], v[172:175], v[156:159], v[28:31]
	v_mfma_f32_16x16x32_bf16 v[24:27], v[176:179], v[140:143], v[24:27]
	v_mfma_f32_16x16x32_bf16 v[24:27], v[180:183], v[156:159], v[24:27]
	v_mfma_f32_16x16x32_bf16 v[20:23], v[184:187], v[136:139], v[20:23]
	v_mfma_f32_16x16x32_bf16 v[20:23], v[188:191], v[152:155], v[20:23]
	v_mfma_f32_16x16x32_bf16 v[16:19], v[192:195], v[136:139], v[16:19]
	v_mfma_f32_16x16x32_bf16 v[16:19], v[196:199], v[152:155], v[16:19]
	v_mfma_f32_16x16x32_bf16 v[12:15], v[168:171], v[136:139], v[12:15]
	v_mfma_f32_16x16x32_bf16 v[12:15], v[172:175], v[152:155], v[12:15]
	v_mfma_f32_16x16x32_bf16 v[8:11], v[176:179], v[136:139], v[8:11]
	v_mfma_f32_16x16x32_bf16 v[8:11], v[180:183], v[152:155], v[8:11]
	s_setprio 0
	s_branch .LBB0_259

.LBB0_369:
	v_add_u32_e32 v168, 0x10000, v232
	v_add_u32_e32 v180, 0x14000, v232
	v_lshl_add_u64 v[224:225], v[222:223], 0, s[60:61]
	s_add_i32 m0, s9, 0xc000
	s_waitcnt lgkmcnt(0)
	ds_read_b128 v[148:151], v207
	ds_read_b128 v[164:167], v207 offset:1024
	ds_read_b128 v[144:147], v207 offset:2048
	ds_read_b128 v[160:163], v207 offset:3072
	ds_read_b128 v[140:143], v207 offset:4096
	ds_read_b128 v[156:159], v207 offset:5120
	ds_read_b128 v[136:139], v207 offset:6144
	ds_read_b128 v[152:155], v207 offset:7168
	ds_read_b128 v[184:187], v168
	ds_read_b128 v[188:191], v168 offset:1024
	ds_read_b128 v[192:195], v168 offset:2048
	ds_read_b128 v[196:199], v168 offset:3072
	ds_read_b128 v[168:171], v180
	ds_read_b128 v[172:175], v180 offset:1024
	ds_read_b128 v[176:179], v180 offset:2048
	ds_read_b128 v[180:183], v180 offset:3072
	global_load_lds_dwordx4 v[224:225], off
	v_lshl_add_u64 v[224:225], v[220:221], 0, s[60:61]
	s_add_i32 m0, s9, 0xe000
	s_nop 0
	global_load_lds_dwordx4 v[224:225], off
	s_waitcnt vmcnt(8)
	s_waitcnt lgkmcnt(0)
	s_barrier
	s_setprio 1
	s_waitcnt lgkmcnt(0)
	v_mfma_f32_16x16x32_bf16 v[132:135], v[184:187], v[148:151], v[132:135]
	v_mfma_f32_16x16x32_bf16 v[132:135], v[188:191], v[164:167], v[132:135]
	v_mfma_f32_16x16x32_bf16 v[128:131], v[192:195], v[148:151], v[128:131]
	v_mfma_f32_16x16x32_bf16 v[128:131], v[196:199], v[164:167], v[128:131]
	v_mfma_f32_16x16x32_bf16 v[116:119], v[168:171], v[148:151], v[116:119]
	v_mfma_f32_16x16x32_bf16 v[116:119], v[172:175], v[164:167], v[116:119]
	v_mfma_f32_16x16x32_bf16 v[112:115], v[176:179], v[148:151], v[112:115]
	v_mfma_f32_16x16x32_bf16 v[112:115], v[180:183], v[164:167], v[112:115]
	v_mfma_f32_16x16x32_bf16 v[124:127], v[184:187], v[144:147], v[124:127]
	v_mfma_f32_16x16x32_bf16 v[124:127], v[188:191], v[160:163], v[124:127]
	v_mfma_f32_16x16x32_bf16 v[120:123], v[192:195], v[144:147], v[120:123]
	v_mfma_f32_16x16x32_bf16 v[120:123], v[196:199], v[160:163], v[120:123]
	v_mfma_f32_16x16x32_bf16 v[100:103], v[168:171], v[144:147], v[100:103]
	v_mfma_f32_16x16x32_bf16 v[100:103], v[172:175], v[160:163], v[100:103]
	v_mfma_f32_16x16x32_bf16 v[96:99], v[176:179], v[144:147], v[96:99]
	v_mfma_f32_16x16x32_bf16 v[96:99], v[180:183], v[160:163], v[96:99]
	s_setprio 0
	s_setprio 1
	v_mfma_f32_16x16x32_bf16 v[108:111], v[184:187], v[140:143], v[108:111]
	v_mfma_f32_16x16x32_bf16 v[108:111], v[188:191], v[156:159], v[108:111]
	v_mfma_f32_16x16x32_bf16 v[104:107], v[192:195], v[140:143], v[104:107]
	v_mfma_f32_16x16x32_bf16 v[104:107], v[196:199], v[156:159], v[104:107]
	v_mfma_f32_16x16x32_bf16 v[84:87], v[168:171], v[140:143], v[84:87]
	v_mfma_f32_16x16x32_bf16 v[84:87], v[172:175], v[156:159], v[84:87]
	v_mfma_f32_16x16x32_bf16 v[80:83], v[176:179], v[140:143], v[80:83]
	v_mfma_f32_16x16x32_bf16 v[80:83], v[180:183], v[156:159], v[80:83]
	v_mfma_f32_16x16x32_bf16 v[92:95], v[184:187], v[136:139], v[92:95]
	v_mfma_f32_16x16x32_bf16 v[92:95], v[188:191], v[152:155], v[92:95]
	v_mfma_f32_16x16x32_bf16 v[88:91], v[192:195], v[136:139], v[88:91]
	v_mfma_f32_16x16x32_bf16 v[88:91], v[196:199], v[152:155], v[88:91]
	v_mfma_f32_16x16x32_bf16 v[76:79], v[168:171], v[136:139], v[76:79]
	v_mfma_f32_16x16x32_bf16 v[76:79], v[172:175], v[152:155], v[76:79]
	v_mfma_f32_16x16x32_bf16 v[72:75], v[176:179], v[136:139], v[72:75]
	v_mfma_f32_16x16x32_bf16 v[72:75], v[180:183], v[152:155], v[72:75]
	s_setprio 0
	s_barrier
	v_cndmask_b32_e64 v204, 0, 1, s[58:59]
	v_cmp_ne_u32_e64 s[50:51], 1, v204
	s_andn2_b64 vcc, exec, s[58:59]
	s_cbranch_vccnz .LBB0_371
	ds_read_b128 v[148:151], v207 offset:16384
	ds_read_b128 v[164:167], v207 offset:17408
	ds_read_b128 v[144:147], v207 offset:18432
	ds_read_b128 v[160:163], v207 offset:19456
	ds_read_b128 v[140:143], v207 offset:20480
	ds_read_b128 v[156:159], v207 offset:21504
	ds_read_b128 v[136:139], v207 offset:22528
	ds_read_b128 v[152:155], v207 offset:23552
.LBB0_371:
	s_add_u32 s12, s24, s60
	s_addc_u32 s13, s25, s61
	s_add_u32 s14, s12, 0x100
	s_addc_u32 s15, s13, 0
	s_add_u32 s73, s26, s60
	s_addc_u32 s74, s27, s61
	s_cmpk_eq_i32 s60, 0xf00
	s_cselect_b64 s[52:53], -1, 0
	s_and_b64 s[12:13], s[52:53], exec
	s_cselect_b32 s13, s37, s74
	s_cselect_b32 s12, s43, s73
	s_mov_b32 m0, s38
	s_cselect_b32 s15, s7, s15
	s_cselect_b32 s14, s33, s14
	v_lshl_add_u64 v[224:225], s[12:13], 0, v[208:209]
	s_add_u32 s74, s12, 0x80000
	global_load_lds_dwordx4 v[224:225], off
	v_lshl_add_u64 v[226:227], s[12:13], 0, v[212:213]
	s_mov_b32 m0, s39
	s_addc_u32 s75, s13, 0
	global_load_lds_dwordx4 v[226:227], off
	v_lshl_add_u64 v[228:229], s[74:75], 0, v[208:209]
	s_mov_b32 m0, s40
	v_lshl_add_u64 v[230:231], s[14:15], 0, v[210:211]
	global_load_lds_dwordx4 v[228:229], off
	v_lshl_add_u64 v[228:229], s[74:75], 0, v[212:213]
	s_mov_b32 m0, s41
	s_and_b64 vcc, exec, s[50:51]
	global_load_lds_dwordx4 v[228:229], off
	v_lshl_add_u64 v[228:229], s[14:15], 0, v[4:5]
	s_mov_b32 m0, s9
	s_nop 0
	global_load_lds_dwordx4 v[228:229], off
	s_mov_b32 m0, s47
	s_nop 0
	global_load_lds_dwordx4 v[230:231], off
	s_waitcnt vmcnt(8)
	s_waitcnt lgkmcnt(0)
	s_barrier
	s_cbranch_vccnz .LBB0_373
	s_setprio 1
	s_waitcnt lgkmcnt(0)
	v_mfma_f32_16x16x32_bf16 v[68:71], v[184:187], v[148:151], v[68:71]
	v_mfma_f32_16x16x32_bf16 v[68:71], v[188:191], v[164:167], v[68:71]
	v_mfma_f32_16x16x32_bf16 v[64:67], v[192:195], v[148:151], v[64:67]
	v_mfma_f32_16x16x32_bf16 v[64:67], v[196:199], v[164:167], v[64:67]
	v_mfma_f32_16x16x32_bf16 v[60:63], v[168:171], v[148:151], v[60:63]
	v_mfma_f32_16x16x32_bf16 v[60:63], v[172:175], v[164:167], v[60:63]
	v_mfma_f32_16x16x32_bf16 v[56:59], v[176:179], v[148:151], v[56:59]
	v_mfma_f32_16x16x32_bf16 v[56:59], v[180:183], v[164:167], v[56:59]
	v_mfma_f32_16x16x32_bf16 v[52:55], v[184:187], v[144:147], v[52:55]
	v_mfma_f32_16x16x32_bf16 v[52:55], v[188:191], v[160:163], v[52:55]
	v_mfma_f32_16x16x32_bf16 v[48:51], v[192:195], v[144:147], v[48:51]
	v_mfma_f32_16x16x32_bf16 v[48:51], v[196:199], v[160:163], v[48:51]
	v_mfma_f32_16x16x32_bf16 v[44:47], v[168:171], v[144:147], v[44:47]
	v_mfma_f32_16x16x32_bf16 v[44:47], v[172:175], v[160:163], v[44:47]
	v_mfma_f32_16x16x32_bf16 v[40:43], v[176:179], v[144:147], v[40:43]
	v_mfma_f32_16x16x32_bf16 v[40:43], v[180:183], v[160:163], v[40:43]
	s_setprio 0
	s_setprio 1
	v_mfma_f32_16x16x32_bf16 v[36:39], v[184:187], v[140:143], v[36:39]
	v_mfma_f32_16x16x32_bf16 v[36:39], v[188:191], v[156:159], v[36:39]
	v_mfma_f32_16x16x32_bf16 v[32:35], v[192:195], v[140:143], v[32:35]
	v_mfma_f32_16x16x32_bf16 v[32:35], v[196:199], v[156:159], v[32:35]
	v_mfma_f32_16x16x32_bf16 v[28:31], v[168:171], v[140:143], v[28:31]
	v_mfma_f32_16x16x32_bf16 v[28:31], v[172:175], v[156:159], v[28:31]
	v_mfma_f32_16x16x32_bf16 v[24:27], v[176:179], v[140:143], v[24:27]
	v_mfma_f32_16x16x32_bf16 v[24:27], v[180:183], v[156:159], v[24:27]
	v_mfma_f32_16x16x32_bf16 v[20:23], v[184:187], v[136:139], v[20:23]
	v_mfma_f32_16x16x32_bf16 v[20:23], v[188:191], v[152:155], v[20:23]
	v_mfma_f32_16x16x32_bf16 v[16:19], v[192:195], v[136:139], v[16:19]
	v_mfma_f32_16x16x32_bf16 v[16:19], v[196:199], v[152:155], v[16:19]
	v_mfma_f32_16x16x32_bf16 v[12:15], v[168:171], v[136:139], v[12:15]
	v_mfma_f32_16x16x32_bf16 v[12:15], v[172:175], v[152:155], v[12:15]
	v_mfma_f32_16x16x32_bf16 v[8:11], v[176:179], v[136:139], v[8:11]
	v_mfma_f32_16x16x32_bf16 v[8:11], v[180:183], v[152:155], v[8:11]
	s_setprio 0
.LBB0_373:
	s_barrier
	v_cndmask_b32_e64 v241, v219, 0, s[52:53]
	v_cndmask_b32_e64 v240, v218, v2, s[52:53]
	v_lshl_add_u64 v[240:241], s[14:15], 0, v[240:241]
	s_mov_b32 m0, s62
	v_add_u32_e32 v168, 0x18000, v232
	v_add_u32_e32 v180, 0x1c000, v232
	v_lshl_add_u64 v[242:243], v[240:241], 0, v[4:5]
	s_waitcnt lgkmcnt(0)
	ds_read_b128 v[148:151], v207 offset:32768
	ds_read_b128 v[164:167], v207 offset:33792
	ds_read_b128 v[144:147], v207 offset:34816
	ds_read_b128 v[160:163], v207 offset:35840
	ds_read_b128 v[140:143], v207 offset:36864
	ds_read_b128 v[156:159], v207 offset:37888
	ds_read_b128 v[136:139], v207 offset:38912
	ds_read_b128 v[152:155], v207 offset:39936
	ds_read_b128 v[184:187], v168
	ds_read_b128 v[188:191], v168 offset:1024
	ds_read_b128 v[192:195], v168 offset:2048
	ds_read_b128 v[196:199], v168 offset:3072
	ds_read_b128 v[168:171], v180
	ds_read_b128 v[172:175], v180 offset:1024
	ds_read_b128 v[176:179], v180 offset:2048
	ds_read_b128 v[180:183], v180 offset:3072
	global_load_lds_dwordx4 v[242:243], off
	v_lshl_add_u64 v[240:241], v[240:241], 0, v[210:211]
	s_mov_b32 m0, s63
	s_nop 0
	global_load_lds_dwordx4 v[240:241], off
	s_waitcnt vmcnt(8)
	s_waitcnt lgkmcnt(0)
	s_barrier
	s_setprio 1
	s_waitcnt lgkmcnt(0)
	v_mfma_f32_16x16x32_bf16 v[132:135], v[184:187], v[148:151], v[132:135]
	v_mfma_f32_16x16x32_bf16 v[132:135], v[188:191], v[164:167], v[132:135]
	v_mfma_f32_16x16x32_bf16 v[128:131], v[192:195], v[148:151], v[128:131]
	v_mfma_f32_16x16x32_bf16 v[128:131], v[196:199], v[164:167], v[128:131]
	v_mfma_f32_16x16x32_bf16 v[116:119], v[168:171], v[148:151], v[116:119]
	v_mfma_f32_16x16x32_bf16 v[116:119], v[172:175], v[164:167], v[116:119]
	v_mfma_f32_16x16x32_bf16 v[112:115], v[176:179], v[148:151], v[112:115]
	v_mfma_f32_16x16x32_bf16 v[112:115], v[180:183], v[164:167], v[112:115]
	v_mfma_f32_16x16x32_bf16 v[124:127], v[184:187], v[144:147], v[124:127]
	v_mfma_f32_16x16x32_bf16 v[124:127], v[188:191], v[160:163], v[124:127]
	v_mfma_f32_16x16x32_bf16 v[120:123], v[192:195], v[144:147], v[120:123]
	v_mfma_f32_16x16x32_bf16 v[120:123], v[196:199], v[160:163], v[120:123]
	v_mfma_f32_16x16x32_bf16 v[100:103], v[168:171], v[144:147], v[100:103]
	v_mfma_f32_16x16x32_bf16 v[100:103], v[172:175], v[160:163], v[100:103]
	v_mfma_f32_16x16x32_bf16 v[96:99], v[176:179], v[144:147], v[96:99]
	v_mfma_f32_16x16x32_bf16 v[96:99], v[180:183], v[160:163], v[96:99]
	s_setprio 0
	s_setprio 1
	v_mfma_f32_16x16x32_bf16 v[108:111], v[184:187], v[140:143], v[108:111]
	v_mfma_f32_16x16x32_bf16 v[108:111], v[188:191], v[156:159], v[108:111]
	v_mfma_f32_16x16x32_bf16 v[104:107], v[192:195], v[140:143], v[104:107]
	v_mfma_f32_16x16x32_bf16 v[104:107], v[196:199], v[156:159], v[104:107]
	v_mfma_f32_16x16x32_bf16 v[84:87], v[168:171], v[140:143], v[84:87]
	v_mfma_f32_16x16x32_bf16 v[84:87], v[172:175], v[156:159], v[84:87]
	v_mfma_f32_16x16x32_bf16 v[80:83], v[176:179], v[140:143], v[80:83]
	v_mfma_f32_16x16x32_bf16 v[80:83], v[180:183], v[156:159], v[80:83]
	v_mfma_f32_16x16x32_bf16 v[92:95], v[184:187], v[136:139], v[92:95]
	v_mfma_f32_16x16x32_bf16 v[92:95], v[188:191], v[152:155], v[92:95]
	v_mfma_f32_16x16x32_bf16 v[88:91], v[192:195], v[136:139], v[88:91]
	v_mfma_f32_16x16x32_bf16 v[88:91], v[196:199], v[152:155], v[88:91]
	v_mfma_f32_16x16x32_bf16 v[76:79], v[168:171], v[136:139], v[76:79]
	v_mfma_f32_16x16x32_bf16 v[76:79], v[172:175], v[152:155], v[76:79]
	v_mfma_f32_16x16x32_bf16 v[72:75], v[176:179], v[136:139], v[72:75]
	v_mfma_f32_16x16x32_bf16 v[72:75], v[180:183], v[152:155], v[72:75]
	s_setprio 0
	s_barrier
	s_and_b64 vcc, exec, s[50:51]
	s_cbranch_vccnz .LBB0_375
	ds_read_b128 v[148:151], v207 offset:49152
	ds_read_b128 v[164:167], v207 offset:50176
	ds_read_b128 v[144:147], v207 offset:51200
	ds_read_b128 v[160:163], v207 offset:52224
	ds_read_b128 v[140:143], v207 offset:53248
	ds_read_b128 v[156:159], v207 offset:54272
	ds_read_b128 v[136:139], v207 offset:55296
	ds_read_b128 v[152:155], v207 offset:56320

.LBB0_559:
	v_add_u32_e32 v168, 0x10000, v240
	v_add_u32_e32 v180, 0x14000, v240
	v_lshl_add_u64 v[226:227], v[224:225], 0, s[64:65]
	s_add_i32 m0, s38, 0xc000
	s_waitcnt lgkmcnt(0)
	ds_read_b128 v[148:151], v239
	ds_read_b128 v[164:167], v239 offset:1024
	ds_read_b128 v[144:147], v239 offset:2048
	ds_read_b128 v[160:163], v239 offset:3072
	ds_read_b128 v[140:143], v239 offset:4096
	ds_read_b128 v[156:159], v239 offset:5120
	ds_read_b128 v[136:139], v239 offset:6144
	ds_read_b128 v[152:155], v239 offset:7168
	ds_read_b128 v[184:187], v168
	ds_read_b128 v[188:191], v168 offset:1024
	ds_read_b128 v[192:195], v168 offset:2048
	ds_read_b128 v[196:199], v168 offset:3072
	ds_read_b128 v[168:171], v180
	ds_read_b128 v[172:175], v180 offset:1024
	ds_read_b128 v[176:179], v180 offset:2048
	ds_read_b128 v[180:183], v180 offset:3072
	global_load_lds_dwordx4 v[226:227], off
	v_lshl_add_u64 v[226:227], v[222:223], 0, s[64:65]
	s_add_i32 m0, s38, 0xe000
	s_nop 0
	global_load_lds_dwordx4 v[226:227], off
	s_waitcnt vmcnt(8)
	s_waitcnt lgkmcnt(0)
	s_barrier
	s_setprio 1
	s_waitcnt lgkmcnt(0)
	v_mfma_f32_16x16x32_bf16 v[132:135], v[184:187], v[148:151], v[132:135]
	v_mfma_f32_16x16x32_bf16 v[132:135], v[188:191], v[164:167], v[132:135]
	v_mfma_f32_16x16x32_bf16 v[128:131], v[192:195], v[148:151], v[128:131]
	v_mfma_f32_16x16x32_bf16 v[128:131], v[196:199], v[164:167], v[128:131]
	v_mfma_f32_16x16x32_bf16 v[124:127], v[168:171], v[148:151], v[124:127]
	v_mfma_f32_16x16x32_bf16 v[124:127], v[172:175], v[164:167], v[124:127]
	v_mfma_f32_16x16x32_bf16 v[120:123], v[176:179], v[148:151], v[120:123]
	v_mfma_f32_16x16x32_bf16 v[120:123], v[180:183], v[164:167], v[120:123]
	v_mfma_f32_16x16x32_bf16 v[116:119], v[184:187], v[144:147], v[116:119]
	v_mfma_f32_16x16x32_bf16 v[116:119], v[188:191], v[160:163], v[116:119]
	v_mfma_f32_16x16x32_bf16 v[112:115], v[192:195], v[144:147], v[112:115]
	v_mfma_f32_16x16x32_bf16 v[112:115], v[196:199], v[160:163], v[112:115]
	v_mfma_f32_16x16x32_bf16 v[108:111], v[168:171], v[144:147], v[108:111]
	v_mfma_f32_16x16x32_bf16 v[108:111], v[172:175], v[160:163], v[108:111]
	v_mfma_f32_16x16x32_bf16 v[104:107], v[176:179], v[144:147], v[104:107]
	v_mfma_f32_16x16x32_bf16 v[104:107], v[180:183], v[160:163], v[104:107]
	s_setprio 0
	s_setprio 1
	v_mfma_f32_16x16x32_bf16 v[100:103], v[184:187], v[140:143], v[100:103]
	v_mfma_f32_16x16x32_bf16 v[100:103], v[188:191], v[156:159], v[100:103]
	v_mfma_f32_16x16x32_bf16 v[96:99], v[192:195], v[140:143], v[96:99]
	v_mfma_f32_16x16x32_bf16 v[96:99], v[196:199], v[156:159], v[96:99]
	v_mfma_f32_16x16x32_bf16 v[92:95], v[168:171], v[140:143], v[92:95]
	v_mfma_f32_16x16x32_bf16 v[92:95], v[172:175], v[156:159], v[92:95]
	v_mfma_f32_16x16x32_bf16 v[88:91], v[176:179], v[140:143], v[88:91]
	v_mfma_f32_16x16x32_bf16 v[88:91], v[180:183], v[156:159], v[88:91]
	v_mfma_f32_16x16x32_bf16 v[84:87], v[184:187], v[136:139], v[84:87]
	v_mfma_f32_16x16x32_bf16 v[84:87], v[188:191], v[152:155], v[84:87]
	v_mfma_f32_16x16x32_bf16 v[80:83], v[192:195], v[136:139], v[80:83]
	v_mfma_f32_16x16x32_bf16 v[80:83], v[196:199], v[152:155], v[80:83]
	v_mfma_f32_16x16x32_bf16 v[76:79], v[168:171], v[136:139], v[76:79]
	v_mfma_f32_16x16x32_bf16 v[76:79], v[172:175], v[152:155], v[76:79]
	v_mfma_f32_16x16x32_bf16 v[72:75], v[176:179], v[136:139], v[72:75]
	v_mfma_f32_16x16x32_bf16 v[72:75], v[180:183], v[152:155], v[72:75]
	s_setprio 0
	s_barrier
	v_cndmask_b32_e64 v204, 0, 1, s[62:63]
	v_cmp_ne_u32_e64 s[50:51], 1, v204
	s_andn2_b64 vcc, exec, s[62:63]
	s_cbranch_vccnz .LBB0_561
	ds_read_b128 v[148:151], v239 offset:16384
	ds_read_b128 v[164:167], v239 offset:17408
	ds_read_b128 v[144:147], v239 offset:18432
	ds_read_b128 v[160:163], v239 offset:19456
	ds_read_b128 v[140:143], v239 offset:20480
	ds_read_b128 v[156:159], v239 offset:21504
	ds_read_b128 v[136:139], v239 offset:22528
	ds_read_b128 v[152:155], v239 offset:23552
.LBB0_561:
	s_add_u32 s12, s60, s64
	s_addc_u32 s13, s61, s65
	s_add_u32 s14, s12, 0x100
	s_addc_u32 s15, s13, 0
	s_add_u32 s79, s26, s64
	s_addc_u32 s80, s27, s65
	s_cmpk_eq_i32 s64, 0x300
	s_cselect_b64 s[52:53], -1, 0
	s_and_b64 s[12:13], s[52:53], exec
	s_cselect_b32 s13, s17, s80
	s_cselect_b32 s12, s35, s79
	s_mov_b32 m0, s39
	s_cselect_b32 s15, s21, s15
	s_cselect_b32 s14, s33, s14
	v_lshl_add_u64 v[226:227], s[12:13], 0, v[4:5]
	s_add_u32 s80, s12, 0x20000
	global_load_lds_dwordx4 v[226:227], off
	v_lshl_add_u64 v[228:229], s[12:13], 0, v[208:209]
	s_mov_b32 m0, s40
	s_addc_u32 s81, s13, 0
	global_load_lds_dwordx4 v[228:229], off
	v_lshl_add_u64 v[230:231], s[80:81], 0, v[4:5]
	s_mov_b32 m0, s41
	v_lshl_add_u64 v[232:233], s[14:15], 0, v[208:209]
	global_load_lds_dwordx4 v[230:231], off
	v_lshl_add_u64 v[230:231], s[80:81], 0, v[208:209]
	s_mov_b32 m0, s47
	s_and_b64 vcc, exec, s[50:51]
	global_load_lds_dwordx4 v[230:231], off
	v_lshl_add_u64 v[230:231], s[14:15], 0, v[4:5]
	s_mov_b32 m0, s38
	s_nop 0
	global_load_lds_dwordx4 v[230:231], off
	s_mov_b32 m0, s59
	s_nop 0
	global_load_lds_dwordx4 v[232:233], off
	s_waitcnt vmcnt(8)
	s_waitcnt lgkmcnt(0)
	s_barrier
	s_cbranch_vccnz .LBB0_563
	s_setprio 1
	s_waitcnt lgkmcnt(0)
	v_mfma_f32_16x16x32_bf16 v[68:71], v[184:187], v[148:151], v[68:71]
	v_mfma_f32_16x16x32_bf16 v[68:71], v[188:191], v[164:167], v[68:71]
	v_mfma_f32_16x16x32_bf16 v[64:67], v[192:195], v[148:151], v[64:67]
	v_mfma_f32_16x16x32_bf16 v[64:67], v[196:199], v[164:167], v[64:67]
	v_mfma_f32_16x16x32_bf16 v[60:63], v[168:171], v[148:151], v[60:63]
	v_mfma_f32_16x16x32_bf16 v[60:63], v[172:175], v[164:167], v[60:63]
	v_mfma_f32_16x16x32_bf16 v[56:59], v[176:179], v[148:151], v[56:59]
	v_mfma_f32_16x16x32_bf16 v[56:59], v[180:183], v[164:167], v[56:59]
	v_mfma_f32_16x16x32_bf16 v[52:55], v[184:187], v[144:147], v[52:55]
	v_mfma_f32_16x16x32_bf16 v[52:55], v[188:191], v[160:163], v[52:55]
	v_mfma_f32_16x16x32_bf16 v[48:51], v[192:195], v[144:147], v[48:51]
	v_mfma_f32_16x16x32_bf16 v[48:51], v[196:199], v[160:163], v[48:51]
	v_mfma_f32_16x16x32_bf16 v[44:47], v[168:171], v[144:147], v[44:47]
	v_mfma_f32_16x16x32_bf16 v[44:47], v[172:175], v[160:163], v[44:47]
	v_mfma_f32_16x16x32_bf16 v[40:43], v[176:179], v[144:147], v[40:43]
	v_mfma_f32_16x16x32_bf16 v[40:43], v[180:183], v[160:163], v[40:43]
	s_setprio 0
	s_setprio 1
	v_mfma_f32_16x16x32_bf16 v[36:39], v[184:187], v[140:143], v[36:39]
	v_mfma_f32_16x16x32_bf16 v[36:39], v[188:191], v[156:159], v[36:39]
	v_mfma_f32_16x16x32_bf16 v[32:35], v[192:195], v[140:143], v[32:35]
	v_mfma_f32_16x16x32_bf16 v[32:35], v[196:199], v[156:159], v[32:35]
	v_mfma_f32_16x16x32_bf16 v[28:31], v[168:171], v[140:143], v[28:31]
	v_mfma_f32_16x16x32_bf16 v[28:31], v[172:175], v[156:159], v[28:31]
	v_mfma_f32_16x16x32_bf16 v[24:27], v[176:179], v[140:143], v[24:27]
	v_mfma_f32_16x16x32_bf16 v[24:27], v[180:183], v[156:159], v[24:27]
	v_mfma_f32_16x16x32_bf16 v[20:23], v[184:187], v[136:139], v[20:23]
	v_mfma_f32_16x16x32_bf16 v[20:23], v[188:191], v[152:155], v[20:23]
	v_mfma_f32_16x16x32_bf16 v[16:19], v[192:195], v[136:139], v[16:19]
	v_mfma_f32_16x16x32_bf16 v[16:19], v[196:199], v[152:155], v[16:19]
	v_mfma_f32_16x16x32_bf16 v[12:15], v[168:171], v[136:139], v[12:15]
	v_mfma_f32_16x16x32_bf16 v[12:15], v[172:175], v[152:155], v[12:15]
	v_mfma_f32_16x16x32_bf16 v[8:11], v[176:179], v[136:139], v[8:11]
	v_mfma_f32_16x16x32_bf16 v[8:11], v[180:183], v[152:155], v[8:11]
	s_setprio 0
.LBB0_563:
	s_barrier
	v_cndmask_b32_e64 v243, v221, 0, s[52:53]
	v_cndmask_b32_e64 v242, v220, v2, s[52:53]
	v_lshl_add_u64 v[242:243], s[14:15], 0, v[242:243]
	s_mov_b32 m0, s66
	v_add_u32_e32 v168, 0x18000, v240
	v_add_u32_e32 v180, 0x1c000, v240
	v_lshl_add_u64 v[204:205], v[242:243], 0, v[4:5]
	s_waitcnt lgkmcnt(0)
	ds_read_b128 v[148:151], v239 offset:32768
	ds_read_b128 v[164:167], v239 offset:33792
	ds_read_b128 v[144:147], v239 offset:34816
	ds_read_b128 v[160:163], v239 offset:35840
	ds_read_b128 v[140:143], v239 offset:36864
	ds_read_b128 v[156:159], v239 offset:37888
	ds_read_b128 v[136:139], v239 offset:38912
	ds_read_b128 v[152:155], v239 offset:39936
	ds_read_b128 v[184:187], v168
	ds_read_b128 v[188:191], v168 offset:1024
	ds_read_b128 v[192:195], v168 offset:2048
	ds_read_b128 v[196:199], v168 offset:3072
	ds_read_b128 v[168:171], v180
	ds_read_b128 v[172:175], v180 offset:1024
	ds_read_b128 v[176:179], v180 offset:2048
	ds_read_b128 v[180:183], v180 offset:3072
	global_load_lds_dwordx4 v[204:205], off
	v_lshl_add_u64 v[204:205], v[242:243], 0, v[208:209]
	s_mov_b32 m0, s67
	s_nop 0
	global_load_lds_dwordx4 v[204:205], off
	s_waitcnt vmcnt(8)
	s_waitcnt lgkmcnt(0)
	s_barrier
	s_setprio 1
	s_waitcnt lgkmcnt(0)
	v_mfma_f32_16x16x32_bf16 v[132:135], v[184:187], v[148:151], v[132:135]
	v_mfma_f32_16x16x32_bf16 v[132:135], v[188:191], v[164:167], v[132:135]
	v_mfma_f32_16x16x32_bf16 v[128:131], v[192:195], v[148:151], v[128:131]
	v_mfma_f32_16x16x32_bf16 v[128:131], v[196:199], v[164:167], v[128:131]
	v_mfma_f32_16x16x32_bf16 v[124:127], v[168:171], v[148:151], v[124:127]
	v_mfma_f32_16x16x32_bf16 v[124:127], v[172:175], v[164:167], v[124:127]
	v_mfma_f32_16x16x32_bf16 v[120:123], v[176:179], v[148:151], v[120:123]
	v_mfma_f32_16x16x32_bf16 v[120:123], v[180:183], v[164:167], v[120:123]
	v_mfma_f32_16x16x32_bf16 v[116:119], v[184:187], v[144:147], v[116:119]
	v_mfma_f32_16x16x32_bf16 v[116:119], v[188:191], v[160:163], v[116:119]
	v_mfma_f32_16x16x32_bf16 v[112:115], v[192:195], v[144:147], v[112:115]
	v_mfma_f32_16x16x32_bf16 v[112:115], v[196:199], v[160:163], v[112:115]
	v_mfma_f32_16x16x32_bf16 v[108:111], v[168:171], v[144:147], v[108:111]
	v_mfma_f32_16x16x32_bf16 v[108:111], v[172:175], v[160:163], v[108:111]
	v_mfma_f32_16x16x32_bf16 v[104:107], v[176:179], v[144:147], v[104:107]
	v_mfma_f32_16x16x32_bf16 v[104:107], v[180:183], v[160:163], v[104:107]
	s_setprio 0
	s_setprio 1
	v_mfma_f32_16x16x32_bf16 v[100:103], v[184:187], v[140:143], v[100:103]
	v_mfma_f32_16x16x32_bf16 v[100:103], v[188:191], v[156:159], v[100:103]
	v_mfma_f32_16x16x32_bf16 v[96:99], v[192:195], v[140:143], v[96:99]
	v_mfma_f32_16x16x32_bf16 v[96:99], v[196:199], v[156:159], v[96:99]
	v_mfma_f32_16x16x32_bf16 v[92:95], v[168:171], v[140:143], v[92:95]
	v_mfma_f32_16x16x32_bf16 v[92:95], v[172:175], v[156:159], v[92:95]
	v_mfma_f32_16x16x32_bf16 v[88:91], v[176:179], v[140:143], v[88:91]
	v_mfma_f32_16x16x32_bf16 v[88:91], v[180:183], v[156:159], v[88:91]
	v_mfma_f32_16x16x32_bf16 v[84:87], v[184:187], v[136:139], v[84:87]
	v_mfma_f32_16x16x32_bf16 v[84:87], v[188:191], v[152:155], v[84:87]
	v_mfma_f32_16x16x32_bf16 v[80:83], v[192:195], v[136:139], v[80:83]
	v_mfma_f32_16x16x32_bf16 v[80:83], v[196:199], v[152:155], v[80:83]
	v_mfma_f32_16x16x32_bf16 v[76:79], v[168:171], v[136:139], v[76:79]
	v_mfma_f32_16x16x32_bf16 v[76:79], v[172:175], v[152:155], v[76:79]
	v_mfma_f32_16x16x32_bf16 v[72:75], v[176:179], v[136:139], v[72:75]
	v_mfma_f32_16x16x32_bf16 v[72:75], v[180:183], v[152:155], v[72:75]
	s_setprio 0
	s_barrier
	s_and_b64 vcc, exec, s[50:51]
	s_cbranch_vccnz .LBB0_565
	ds_read_b128 v[148:151], v239 offset:49152
	ds_read_b128 v[164:167], v239 offset:50176
	ds_read_b128 v[144:147], v239 offset:51200
	ds_read_b128 v[160:163], v239 offset:52224
	ds_read_b128 v[140:143], v239 offset:53248
	ds_read_b128 v[156:159], v239 offset:54272
	ds_read_b128 v[136:139], v239 offset:55296
	ds_read_b128 v[152:155], v239 offset:56320
.LBB0_565:
	s_mov_b32 m0, s70
	v_lshl_add_u64 v[204:205], v[226:227], 0, s[0:1]
	s_add_u32 s12, s12, 0x20080
	global_load_lds_dwordx4 v[204:205], off
	v_lshl_add_u64 v[204:205], v[228:229], 0, s[0:1]
	s_mov_b32 m0, s71
	s_addc_u32 s13, s13, 0
	global_load_lds_dwordx4 v[204:205], off
	v_lshl_add_u64 v[204:205], s[12:13], 0, v[4:5]
	s_mov_b32 m0, s74
	s_and_b64 vcc, exec, s[50:51]
	global_load_lds_dwordx4 v[204:205], off
	v_lshl_add_u64 v[204:205], s[12:13], 0, v[208:209]
	s_mov_b32 m0, s75
	s_nop 0
	global_load_lds_dwordx4 v[204:205], off
	v_lshl_add_u64 v[204:205], v[230:231], 0, s[0:1]
	s_mov_b32 m0, s72
	s_nop 0
	global_load_lds_dwordx4 v[204:205], off
	v_lshl_add_u64 v[204:205], v[232:233], 0, s[0:1]
	s_mov_b32 m0, s73
	s_nop 0
	global_load_lds_dwordx4 v[204:205], off
	s_waitcnt vmcnt(8)
	s_waitcnt lgkmcnt(0)
	s_barrier
	s_cbranch_vccnz .LBB0_558
	s_setprio 1
	s_waitcnt lgkmcnt(0)
	v_mfma_f32_16x16x32_bf16 v[68:71], v[184:187], v[148:151], v[68:71]
	v_mfma_f32_16x16x32_bf16 v[68:71], v[188:191], v[164:167], v[68:71]
	v_mfma_f32_16x16x32_bf16 v[64:67], v[192:195], v[148:151], v[64:67]
	v_mfma_f32_16x16x32_bf16 v[64:67], v[196:199], v[164:167], v[64:67]
	v_mfma_f32_16x16x32_bf16 v[60:63], v[168:171], v[148:151], v[60:63]
	v_mfma_f32_16x16x32_bf16 v[60:63], v[172:175], v[164:167], v[60:63]
	v_mfma_f32_16x16x32_bf16 v[56:59], v[176:179], v[148:151], v[56:59]
	v_mfma_f32_16x16x32_bf16 v[56:59], v[180:183], v[164:167], v[56:59]
	v_mfma_f32_16x16x32_bf16 v[52:55], v[184:187], v[144:147], v[52:55]
	v_mfma_f32_16x16x32_bf16 v[52:55], v[188:191], v[160:163], v[52:55]
	v_mfma_f32_16x16x32_bf16 v[48:51], v[192:195], v[144:147], v[48:51]
	v_mfma_f32_16x16x32_bf16 v[48:51], v[196:199], v[160:163], v[48:51]
	v_mfma_f32_16x16x32_bf16 v[44:47], v[168:171], v[144:147], v[44:47]
	v_mfma_f32_16x16x32_bf16 v[44:47], v[172:175], v[160:163], v[44:47]
	v_mfma_f32_16x16x32_bf16 v[40:43], v[176:179], v[144:147], v[40:43]
	v_mfma_f32_16x16x32_bf16 v[40:43], v[180:183], v[160:163], v[40:43]
	s_setprio 0
	s_setprio 1
	v_mfma_f32_16x16x32_bf16 v[36:39], v[184:187], v[140:143], v[36:39]
	v_mfma_f32_16x16x32_bf16 v[36:39], v[188:191], v[156:159], v[36:39]
	v_mfma_f32_16x16x32_bf16 v[32:35], v[192:195], v[140:143], v[32:35]
	v_mfma_f32_16x16x32_bf16 v[32:35], v[196:199], v[156:159], v[32:35]
	v_mfma_f32_16x16x32_bf16 v[28:31], v[168:171], v[140:143], v[28:31]
	v_mfma_f32_16x16x32_bf16 v[28:31], v[172:175], v[156:159], v[28:31]
	v_mfma_f32_16x16x32_bf16 v[24:27], v[176:179], v[140:143], v[24:27]
	v_mfma_f32_16x16x32_bf16 v[24:27], v[180:183], v[156:159], v[24:27]
	v_mfma_f32_16x16x32_bf16 v[20:23], v[184:187], v[136:139], v[20:23]
	v_mfma_f32_16x16x32_bf16 v[20:23], v[188:191], v[152:155], v[20:23]
	v_mfma_f32_16x16x32_bf16 v[16:19], v[192:195], v[136:139], v[16:19]
	v_mfma_f32_16x16x32_bf16 v[16:19], v[196:199], v[152:155], v[16:19]
	v_mfma_f32_16x16x32_bf16 v[12:15], v[168:171], v[136:139], v[12:15]
	v_mfma_f32_16x16x32_bf16 v[12:15], v[172:175], v[152:155], v[12:15]
	v_mfma_f32_16x16x32_bf16 v[8:11], v[176:179], v[136:139], v[8:11]
	v_mfma_f32_16x16x32_bf16 v[8:11], v[180:183], v[152:155], v[8:11]
	s_setprio 0
	s_branch .LBB0_558

.LBB0_620:
	s_add_u32 s12, s42, 0xfffe0080
	s_addc_u32 s13, s43, -1
	s_cmp_eq_u32 s57, 4
	s_cselect_b32 s15, s17, s13
	s_cselect_b32 s14, s33, s12
	s_cselect_b32 s13, s11, s27
	s_cselect_b32 s12, s37, s26
	s_add_i32 s58, 0, 0x10000
	v_add_u32_e32 v136, s58, v1
	s_add_i32 s60, 0, 0x14000
	ds_read_b128 v[150:153], v7
	ds_read_b128 v[154:157], v7 offset:1024
	ds_read_b128 v[158:161], v7 offset:2048
	ds_read_b128 v[162:165], v7 offset:3072
	ds_read_b128 v[166:169], v7 offset:4096
	ds_read_b128 v[170:173], v7 offset:5120
	ds_read_b128 v[174:177], v7 offset:6144
	ds_read_b128 v[178:181], v7 offset:7168
	ds_read_b128 v[182:185], v136
	ds_read_b128 v[186:189], v136 offset:1024
	ds_read_b128 v[190:193], v136 offset:2048
	ds_read_b128 v[194:197], v136 offset:3072
	v_add_u32_e32 v136, s60, v1
	ds_read_b128 v[208:211], v136
	ds_read_b128 v[212:215], v136 offset:1024
	ds_read_b128 v[216:219], v136 offset:2048
	ds_read_b128 v[220:223], v136 offset:3072
	v_lshl_add_u64 v[136:137], s[42:43], 0, v[146:147]
	s_add_i32 m0, s38, 0xc000
	s_nop 0
	global_load_lds_dwordx4 v[136:137], off
	v_lshl_add_u64 v[136:137], s[42:43], 0, v[148:149]
	s_add_i32 m0, s38, 0xe000
	s_nop 0
	global_load_lds_dwordx4 v[136:137], off
	s_waitcnt vmcnt(8)
	s_waitcnt lgkmcnt(0)
	s_barrier
	s_setprio 1
	s_waitcnt lgkmcnt(0)
	v_mfma_f32_16x16x32_bf16 v[132:135], v[182:185], v[150:153], v[132:135]
	v_mfma_f32_16x16x32_bf16 v[132:135], v[186:189], v[154:157], v[132:135]
	v_mfma_f32_16x16x32_bf16 v[128:131], v[190:193], v[150:153], v[128:131]
	v_mfma_f32_16x16x32_bf16 v[128:131], v[194:197], v[154:157], v[128:131]
	v_mfma_f32_16x16x32_bf16 v[112:115], v[208:211], v[150:153], v[112:115]
	v_mfma_f32_16x16x32_bf16 v[112:115], v[212:215], v[154:157], v[112:115]
	v_mfma_f32_16x16x32_bf16 v[104:107], v[216:219], v[150:153], v[104:107]
	v_mfma_f32_16x16x32_bf16 v[104:107], v[220:223], v[154:157], v[104:107]
	v_mfma_f32_16x16x32_bf16 v[124:127], v[182:185], v[158:161], v[124:127]
	v_mfma_f32_16x16x32_bf16 v[124:127], v[186:189], v[162:165], v[124:127]
	v_mfma_f32_16x16x32_bf16 v[120:123], v[190:193], v[158:161], v[120:123]
	v_mfma_f32_16x16x32_bf16 v[120:123], v[194:197], v[162:165], v[120:123]
	v_mfma_f32_16x16x32_bf16 v[96:99], v[208:211], v[158:161], v[96:99]
	v_mfma_f32_16x16x32_bf16 v[96:99], v[212:215], v[162:165], v[96:99]
	v_mfma_f32_16x16x32_bf16 v[88:91], v[216:219], v[158:161], v[88:91]
	v_mfma_f32_16x16x32_bf16 v[88:91], v[220:223], v[162:165], v[88:91]
	s_setprio 0
	s_setprio 1
	v_mfma_f32_16x16x32_bf16 v[116:119], v[182:185], v[166:169], v[116:119]
	v_mfma_f32_16x16x32_bf16 v[116:119], v[186:189], v[170:173], v[116:119]
	v_mfma_f32_16x16x32_bf16 v[108:111], v[190:193], v[166:169], v[108:111]
	v_mfma_f32_16x16x32_bf16 v[108:111], v[194:197], v[170:173], v[108:111]
	v_mfma_f32_16x16x32_bf16 v[84:87], v[208:211], v[166:169], v[84:87]
	v_mfma_f32_16x16x32_bf16 v[84:87], v[212:215], v[170:173], v[84:87]
	v_mfma_f32_16x16x32_bf16 v[80:83], v[216:219], v[166:169], v[80:83]
	v_mfma_f32_16x16x32_bf16 v[80:83], v[220:223], v[170:173], v[80:83]
	v_mfma_f32_16x16x32_bf16 v[100:103], v[182:185], v[174:177], v[100:103]
	v_mfma_f32_16x16x32_bf16 v[100:103], v[186:189], v[178:181], v[100:103]
	v_mfma_f32_16x16x32_bf16 v[92:95], v[190:193], v[174:177], v[92:95]
	v_mfma_f32_16x16x32_bf16 v[92:95], v[194:197], v[178:181], v[92:95]
	v_mfma_f32_16x16x32_bf16 v[76:79], v[208:211], v[174:177], v[76:79]
	v_mfma_f32_16x16x32_bf16 v[76:79], v[212:215], v[178:181], v[76:79]
	v_mfma_f32_16x16x32_bf16 v[72:75], v[216:219], v[174:177], v[72:75]
	v_mfma_f32_16x16x32_bf16 v[72:75], v[220:223], v[178:181], v[72:75]
	s_setprio 0
	s_barrier
	s_add_i32 s58, s58, s35
	v_lshl_add_u64 v[136:137], s[12:13], 0, v[2:3]
	s_mov_b32 m0, s58
	ds_read_b128 v[150:153], v7 offset:16384
	ds_read_b128 v[154:157], v7 offset:17408
	ds_read_b128 v[158:161], v7 offset:18432
	ds_read_b128 v[162:165], v7 offset:19456
	ds_read_b128 v[166:169], v7 offset:20480
	ds_read_b128 v[170:173], v7 offset:21504
	ds_read_b128 v[174:177], v7 offset:22528
	ds_read_b128 v[178:181], v7 offset:23552
	global_load_lds_dwordx4 v[136:137], off
	s_add_i32 m0, s58, 0x2000
	s_add_u32 s58, s12, 0x20000
	v_lshl_add_u64 v[198:199], s[12:13], 0, v[4:5]
	s_addc_u32 s59, s13, 0
	s_add_i32 s60, s60, s35
	global_load_lds_dwordx4 v[198:199], off
	v_lshl_add_u64 v[204:205], s[58:59], 0, v[2:3]
	s_mov_b32 m0, s60
	v_lshl_add_u64 v[224:225], s[14:15], 0, v[138:139]
	global_load_lds_dwordx4 v[204:205], off
	v_lshl_add_u64 v[204:205], s[58:59], 0, v[4:5]
	s_add_i32 m0, s60, 0x2000
	s_nop 0
	global_load_lds_dwordx4 v[204:205], off
	v_lshl_add_u64 v[204:205], s[14:15], 0, v[140:141]
	s_mov_b32 m0, s38
	s_nop 0
	global_load_lds_dwordx4 v[204:205], off
	s_mov_b32 m0, s39
	s_nop 0
	global_load_lds_dwordx4 v[224:225], off
	s_waitcnt vmcnt(8)
	s_waitcnt lgkmcnt(0)
	s_barrier
	s_setprio 1
	s_waitcnt lgkmcnt(0)
	v_mfma_f32_16x16x32_bf16 v[68:71], v[182:185], v[150:153], v[68:71]
	v_mfma_f32_16x16x32_bf16 v[68:71], v[186:189], v[154:157], v[68:71]
	v_mfma_f32_16x16x32_bf16 v[64:67], v[190:193], v[150:153], v[64:67]
	v_mfma_f32_16x16x32_bf16 v[64:67], v[194:197], v[154:157], v[64:67]
	v_mfma_f32_16x16x32_bf16 v[48:51], v[208:211], v[150:153], v[48:51]
	v_mfma_f32_16x16x32_bf16 v[48:51], v[212:215], v[154:157], v[48:51]
	v_mfma_f32_16x16x32_bf16 v[40:43], v[216:219], v[150:153], v[40:43]
	v_mfma_f32_16x16x32_bf16 v[40:43], v[220:223], v[154:157], v[40:43]
	v_mfma_f32_16x16x32_bf16 v[60:63], v[182:185], v[158:161], v[60:63]
	v_mfma_f32_16x16x32_bf16 v[60:63], v[186:189], v[162:165], v[60:63]
	v_mfma_f32_16x16x32_bf16 v[56:59], v[190:193], v[158:161], v[56:59]
	v_mfma_f32_16x16x32_bf16 v[56:59], v[194:197], v[162:165], v[56:59]
	v_mfma_f32_16x16x32_bf16 v[32:35], v[208:211], v[158:161], v[32:35]
	v_mfma_f32_16x16x32_bf16 v[32:35], v[212:215], v[162:165], v[32:35]
	v_mfma_f32_16x16x32_bf16 v[24:27], v[216:219], v[158:161], v[24:27]
	v_mfma_f32_16x16x32_bf16 v[24:27], v[220:223], v[162:165], v[24:27]
	s_setprio 0
	s_setprio 1
	v_mfma_f32_16x16x32_bf16 v[52:55], v[182:185], v[166:169], v[52:55]
	v_mfma_f32_16x16x32_bf16 v[52:55], v[186:189], v[170:173], v[52:55]
	v_mfma_f32_16x16x32_bf16 v[44:47], v[190:193], v[166:169], v[44:47]
	v_mfma_f32_16x16x32_bf16 v[44:47], v[194:197], v[170:173], v[44:47]
	v_mfma_f32_16x16x32_bf16 v[20:23], v[208:211], v[166:169], v[20:23]
	v_mfma_f32_16x16x32_bf16 v[20:23], v[212:215], v[170:173], v[20:23]
	v_mfma_f32_16x16x32_bf16 v[16:19], v[216:219], v[166:169], v[16:19]
	v_mfma_f32_16x16x32_bf16 v[16:19], v[220:223], v[170:173], v[16:19]
	v_mfma_f32_16x16x32_bf16 v[36:39], v[182:185], v[174:177], v[36:39]
	v_mfma_f32_16x16x32_bf16 v[36:39], v[186:189], v[178:181], v[36:39]
	v_mfma_f32_16x16x32_bf16 v[28:31], v[190:193], v[174:177], v[28:31]
	v_mfma_f32_16x16x32_bf16 v[28:31], v[194:197], v[178:181], v[28:31]
	v_mfma_f32_16x16x32_bf16 v[12:15], v[208:211], v[174:177], v[12:15]
	v_mfma_f32_16x16x32_bf16 v[12:15], v[212:215], v[178:181], v[12:15]
	v_mfma_f32_16x16x32_bf16 v[8:11], v[216:219], v[174:177], v[8:11]
	v_mfma_f32_16x16x32_bf16 v[8:11], v[220:223], v[178:181], v[8:11]
	s_setprio 0
	s_barrier
	s_add_i32 s58, 0, 0x18000
	s_add_i32 s59, 0, 0x1c000
	s_add_u32 s14, s14, 0x20000
	s_addc_u32 s15, s15, 0
	s_mov_b32 m0, s40
	v_add_u32_e32 v194, s58, v1
	v_add_u32_e32 v207, s59, v1
	v_lshl_add_u64 v[226:227], s[14:15], 0, v[140:141]
	ds_read_b128 v[150:153], v7 offset:32768
	ds_read_b128 v[154:157], v7 offset:33792
	ds_read_b128 v[158:161], v7 offset:34816
	ds_read_b128 v[162:165], v7 offset:35840
	ds_read_b128 v[166:169], v7 offset:36864
	ds_read_b128 v[170:173], v7 offset:37888
	ds_read_b128 v[174:177], v7 offset:38912
	ds_read_b128 v[178:181], v7 offset:39936
	ds_read_b128 v[182:185], v194
	ds_read_b128 v[186:189], v194 offset:1024
	ds_read_b128 v[190:193], v194 offset:2048
	ds_read_b128 v[194:197], v194 offset:3072
	ds_read_b128 v[208:211], v207
	ds_read_b128 v[212:215], v207 offset:1024
	ds_read_b128 v[216:219], v207 offset:2048
	ds_read_b128 v[220:223], v207 offset:3072
	global_load_lds_dwordx4 v[226:227], off
	v_lshl_add_u64 v[226:227], s[14:15], 0, v[138:139]
	s_mov_b32 m0, s41
	s_nop 0
	global_load_lds_dwordx4 v[226:227], off
	s_waitcnt vmcnt(8)
	s_waitcnt lgkmcnt(0)
	s_barrier
	s_setprio 1
	s_waitcnt lgkmcnt(0)
	v_mfma_f32_16x16x32_bf16 v[132:135], v[182:185], v[150:153], v[132:135]
	v_mfma_f32_16x16x32_bf16 v[132:135], v[186:189], v[154:157], v[132:135]
	v_mfma_f32_16x16x32_bf16 v[128:131], v[190:193], v[150:153], v[128:131]
	v_mfma_f32_16x16x32_bf16 v[128:131], v[194:197], v[154:157], v[128:131]
	v_mfma_f32_16x16x32_bf16 v[112:115], v[208:211], v[150:153], v[112:115]
	v_mfma_f32_16x16x32_bf16 v[112:115], v[212:215], v[154:157], v[112:115]
	v_mfma_f32_16x16x32_bf16 v[104:107], v[216:219], v[150:153], v[104:107]
	v_mfma_f32_16x16x32_bf16 v[104:107], v[220:223], v[154:157], v[104:107]
	v_mfma_f32_16x16x32_bf16 v[124:127], v[182:185], v[158:161], v[124:127]
	v_mfma_f32_16x16x32_bf16 v[124:127], v[186:189], v[162:165], v[124:127]
	v_mfma_f32_16x16x32_bf16 v[120:123], v[190:193], v[158:161], v[120:123]
	v_mfma_f32_16x16x32_bf16 v[120:123], v[194:197], v[162:165], v[120:123]
	v_mfma_f32_16x16x32_bf16 v[96:99], v[208:211], v[158:161], v[96:99]
	v_mfma_f32_16x16x32_bf16 v[96:99], v[212:215], v[162:165], v[96:99]
	v_mfma_f32_16x16x32_bf16 v[88:91], v[216:219], v[158:161], v[88:91]
	v_mfma_f32_16x16x32_bf16 v[88:91], v[220:223], v[162:165], v[88:91]
	s_setprio 0
	s_setprio 1
	v_mfma_f32_16x16x32_bf16 v[116:119], v[182:185], v[166:169], v[116:119]
	v_mfma_f32_16x16x32_bf16 v[116:119], v[186:189], v[170:173], v[116:119]
	v_mfma_f32_16x16x32_bf16 v[108:111], v[190:193], v[166:169], v[108:111]
	v_mfma_f32_16x16x32_bf16 v[108:111], v[194:197], v[170:173], v[108:111]
	v_mfma_f32_16x16x32_bf16 v[84:87], v[208:211], v[166:169], v[84:87]
	v_mfma_f32_16x16x32_bf16 v[84:87], v[212:215], v[170:173], v[84:87]
	v_mfma_f32_16x16x32_bf16 v[80:83], v[216:219], v[166:169], v[80:83]
	v_mfma_f32_16x16x32_bf16 v[80:83], v[220:223], v[170:173], v[80:83]
	v_mfma_f32_16x16x32_bf16 v[100:103], v[182:185], v[174:177], v[100:103]
	v_mfma_f32_16x16x32_bf16 v[100:103], v[186:189], v[178:181], v[100:103]
	v_mfma_f32_16x16x32_bf16 v[92:95], v[190:193], v[174:177], v[92:95]
	v_mfma_f32_16x16x32_bf16 v[92:95], v[194:197], v[178:181], v[92:95]
	v_mfma_f32_16x16x32_bf16 v[76:79], v[208:211], v[174:177], v[76:79]
	v_mfma_f32_16x16x32_bf16 v[76:79], v[212:215], v[178:181], v[76:79]
	v_mfma_f32_16x16x32_bf16 v[72:75], v[216:219], v[174:177], v[72:75]
	v_mfma_f32_16x16x32_bf16 v[72:75], v[220:223], v[178:181], v[72:75]
	s_setprio 0
	s_barrier
	s_add_i32 s14, s58, s35
	v_lshl_add_u64 v[136:137], v[136:137], 0, s[0:1]
	s_mov_b32 m0, s14
	ds_read_b128 v[150:153], v7 offset:49152
	ds_read_b128 v[154:157], v7 offset:50176
	ds_read_b128 v[158:161], v7 offset:51200
	ds_read_b128 v[162:165], v7 offset:52224
	ds_read_b128 v[166:169], v7 offset:53248
	ds_read_b128 v[170:173], v7 offset:54272
	ds_read_b128 v[174:177], v7 offset:55296
	ds_read_b128 v[178:181], v7 offset:56320
	global_load_lds_dwordx4 v[136:137], off
	s_add_i32 m0, s14, 0x2000
	s_add_u32 s12, s12, 0x20080
	v_lshl_add_u64 v[136:137], v[198:199], 0, s[0:1]
	s_addc_u32 s13, s13, 0
	s_add_i32 s14, s59, s35
	global_load_lds_dwordx4 v[136:137], off
	v_lshl_add_u64 v[136:137], s[12:13], 0, v[2:3]
	s_mov_b32 m0, s14
	s_nop 0
	global_load_lds_dwordx4 v[136:137], off
	v_lshl_add_u64 v[136:137], s[12:13], 0, v[4:5]
	s_add_i32 m0, s14, 0x2000
	s_nop 0
	global_load_lds_dwordx4 v[136:137], off
	v_lshl_add_u64 v[136:137], v[204:205], 0, s[0:1]
	s_mov_b32 m0, s49
	s_nop 0
	global_load_lds_dwordx4 v[136:137], off
	v_lshl_add_u64 v[136:137], v[224:225], 0, s[0:1]
	s_mov_b32 m0, s52
	s_nop 0
	global_load_lds_dwordx4 v[136:137], off
	s_waitcnt vmcnt(8)
	s_waitcnt lgkmcnt(0)
	s_barrier
	s_setprio 1
	s_waitcnt lgkmcnt(0)
	v_mfma_f32_16x16x32_bf16 v[68:71], v[182:185], v[150:153], v[68:71]
	v_mfma_f32_16x16x32_bf16 v[68:71], v[186:189], v[154:157], v[68:71]
	v_mfma_f32_16x16x32_bf16 v[64:67], v[190:193], v[150:153], v[64:67]
	v_mfma_f32_16x16x32_bf16 v[64:67], v[194:197], v[154:157], v[64:67]
	v_mfma_f32_16x16x32_bf16 v[48:51], v[208:211], v[150:153], v[48:51]
	v_mfma_f32_16x16x32_bf16 v[48:51], v[212:215], v[154:157], v[48:51]
	v_mfma_f32_16x16x32_bf16 v[40:43], v[216:219], v[150:153], v[40:43]
	v_mfma_f32_16x16x32_bf16 v[40:43], v[220:223], v[154:157], v[40:43]
	v_mfma_f32_16x16x32_bf16 v[60:63], v[182:185], v[158:161], v[60:63]
	v_mfma_f32_16x16x32_bf16 v[60:63], v[186:189], v[162:165], v[60:63]
	v_mfma_f32_16x16x32_bf16 v[56:59], v[190:193], v[158:161], v[56:59]
	v_mfma_f32_16x16x32_bf16 v[56:59], v[194:197], v[162:165], v[56:59]
	v_mfma_f32_16x16x32_bf16 v[32:35], v[208:211], v[158:161], v[32:35]
	v_mfma_f32_16x16x32_bf16 v[32:35], v[212:215], v[162:165], v[32:35]
	v_mfma_f32_16x16x32_bf16 v[24:27], v[216:219], v[158:161], v[24:27]
	v_mfma_f32_16x16x32_bf16 v[24:27], v[220:223], v[162:165], v[24:27]
	s_setprio 0
	s_setprio 1
	v_mfma_f32_16x16x32_bf16 v[52:55], v[182:185], v[166:169], v[52:55]
	v_mfma_f32_16x16x32_bf16 v[52:55], v[186:189], v[170:173], v[52:55]
	v_mfma_f32_16x16x32_bf16 v[44:47], v[190:193], v[166:169], v[44:47]
	v_mfma_f32_16x16x32_bf16 v[44:47], v[194:197], v[170:173], v[44:47]
	v_mfma_f32_16x16x32_bf16 v[20:23], v[208:211], v[166:169], v[20:23]
	v_mfma_f32_16x16x32_bf16 v[20:23], v[212:215], v[170:173], v[20:23]
	v_mfma_f32_16x16x32_bf16 v[16:19], v[216:219], v[166:169], v[16:19]
	v_mfma_f32_16x16x32_bf16 v[16:19], v[220:223], v[170:173], v[16:19]
	v_mfma_f32_16x16x32_bf16 v[36:39], v[182:185], v[174:177], v[36:39]
	v_mfma_f32_16x16x32_bf16 v[36:39], v[186:189], v[178:181], v[36:39]
	v_mfma_f32_16x16x32_bf16 v[28:31], v[190:193], v[174:177], v[28:31]
	v_mfma_f32_16x16x32_bf16 v[28:31], v[194:197], v[178:181], v[28:31]
	v_mfma_f32_16x16x32_bf16 v[12:15], v[208:211], v[174:177], v[12:15]
	v_mfma_f32_16x16x32_bf16 v[12:15], v[212:215], v[178:181], v[12:15]
	v_mfma_f32_16x16x32_bf16 v[8:11], v[216:219], v[174:177], v[8:11]
	v_mfma_f32_16x16x32_bf16 v[8:11], v[220:223], v[178:181], v[8:11]
	s_setprio 0
	s_barrier
	s_add_i32 s57, s57, 2
	s_add_u32 s42, s42, 0x100
	s_addc_u32 s43, s43, 0
	s_add_u32 s26, s26, 0x100
	s_addc_u32 s27, s27, 0
	s_cmp_gt_u32 s57, 5
	s_cbranch_scc0 .LBB0_620
	s_and_b64 vcc, exec, s[6:7]
	s_cbranch_vccz .LBB0_623
	s_barrier

.LBB0_986:
	s_add_u32 s12, s44, 0xfff80080
	s_addc_u32 s13, s45, -1
	s_cmp_eq_u32 s50, 28
	s_cselect_b32 s15, s18, s13
	s_cselect_b32 s14, s19, s12
	s_cselect_b32 s13, s17, s43
	s_cselect_b32 s12, s21, s33
	s_add_i32 s51, 0, 0x10000
	v_add_u32_e32 v2, s51, v7
	s_add_i32 s63, 0, 0x14000
	ds_read_b128 v[150:153], v155
	ds_read_b128 v[156:159], v155 offset:1024
	ds_read_b128 v[160:163], v155 offset:2048
	ds_read_b128 v[164:167], v155 offset:3072
	ds_read_b128 v[168:171], v155 offset:4096
	ds_read_b128 v[172:175], v155 offset:5120
	ds_read_b128 v[176:179], v155 offset:6144
	ds_read_b128 v[180:183], v155 offset:7168
	ds_read_b128 v[184:187], v2
	ds_read_b128 v[188:191], v2 offset:1024
	ds_read_b128 v[192:195], v2 offset:2048
	ds_read_b128 v[196:199], v2 offset:3072
	v_add_u32_e32 v2, s63, v7
	v_lshl_add_u64 v[224:225], s[44:45], 0, v[146:147]
	s_add_i32 m0, s39, 0xc000
	ds_read_b128 v[208:211], v2
	ds_read_b128 v[212:215], v2 offset:1024
	ds_read_b128 v[216:219], v2 offset:2048
	ds_read_b128 v[220:223], v2 offset:3072
	global_load_lds_dwordx4 v[224:225], off
	v_lshl_add_u64 v[224:225], s[44:45], 0, v[148:149]
	s_add_i32 m0, s39, 0xe000
	s_nop 0
	global_load_lds_dwordx4 v[224:225], off
	s_waitcnt vmcnt(8)
	s_waitcnt lgkmcnt(0)
	s_barrier
	s_setprio 1
	s_waitcnt lgkmcnt(0)
	v_mfma_f32_16x16x32_bf16 v[132:135], v[184:187], v[150:153], v[132:135]
	v_mfma_f32_16x16x32_bf16 v[132:135], v[188:191], v[156:159], v[132:135]
	v_mfma_f32_16x16x32_bf16 v[128:131], v[192:195], v[150:153], v[128:131]
	v_mfma_f32_16x16x32_bf16 v[128:131], v[196:199], v[156:159], v[128:131]
	v_mfma_f32_16x16x32_bf16 v[124:127], v[208:211], v[150:153], v[124:127]
	v_mfma_f32_16x16x32_bf16 v[124:127], v[212:215], v[156:159], v[124:127]
	v_mfma_f32_16x16x32_bf16 v[120:123], v[216:219], v[150:153], v[120:123]
	v_mfma_f32_16x16x32_bf16 v[120:123], v[220:223], v[156:159], v[120:123]
	v_mfma_f32_16x16x32_bf16 v[116:119], v[184:187], v[160:163], v[116:119]
	v_mfma_f32_16x16x32_bf16 v[116:119], v[188:191], v[164:167], v[116:119]
	v_mfma_f32_16x16x32_bf16 v[112:115], v[192:195], v[160:163], v[112:115]
	v_mfma_f32_16x16x32_bf16 v[112:115], v[196:199], v[164:167], v[112:115]
	v_mfma_f32_16x16x32_bf16 v[108:111], v[208:211], v[160:163], v[108:111]
	v_mfma_f32_16x16x32_bf16 v[108:111], v[212:215], v[164:167], v[108:111]
	v_mfma_f32_16x16x32_bf16 v[104:107], v[216:219], v[160:163], v[104:107]
	v_mfma_f32_16x16x32_bf16 v[104:107], v[220:223], v[164:167], v[104:107]
	s_setprio 0
	s_setprio 1
	v_mfma_f32_16x16x32_bf16 v[100:103], v[184:187], v[168:171], v[100:103]
	v_mfma_f32_16x16x32_bf16 v[100:103], v[188:191], v[172:175], v[100:103]
	v_mfma_f32_16x16x32_bf16 v[96:99], v[192:195], v[168:171], v[96:99]
	v_mfma_f32_16x16x32_bf16 v[96:99], v[196:199], v[172:175], v[96:99]
	v_mfma_f32_16x16x32_bf16 v[92:95], v[208:211], v[168:171], v[92:95]
	v_mfma_f32_16x16x32_bf16 v[92:95], v[212:215], v[172:175], v[92:95]
	v_mfma_f32_16x16x32_bf16 v[88:91], v[216:219], v[168:171], v[88:91]
	v_mfma_f32_16x16x32_bf16 v[88:91], v[220:223], v[172:175], v[88:91]
	v_mfma_f32_16x16x32_bf16 v[84:87], v[184:187], v[176:179], v[84:87]
	v_mfma_f32_16x16x32_bf16 v[84:87], v[188:191], v[180:183], v[84:87]
	v_mfma_f32_16x16x32_bf16 v[80:83], v[192:195], v[176:179], v[80:83]
	v_mfma_f32_16x16x32_bf16 v[80:83], v[196:199], v[180:183], v[80:83]
	v_mfma_f32_16x16x32_bf16 v[76:79], v[208:211], v[176:179], v[76:79]
	v_mfma_f32_16x16x32_bf16 v[76:79], v[212:215], v[180:183], v[76:79]
	v_mfma_f32_16x16x32_bf16 v[72:75], v[216:219], v[176:179], v[72:75]
	v_mfma_f32_16x16x32_bf16 v[72:75], v[220:223], v[180:183], v[72:75]
	s_setprio 0
	s_barrier
	s_add_i32 s51, s51, s38
	v_lshl_add_u64 v[224:225], s[12:13], 0, v[138:139]
	s_mov_b32 m0, s51
	ds_read_b128 v[150:153], v155 offset:16384
	ds_read_b128 v[156:159], v155 offset:17408
	ds_read_b128 v[160:163], v155 offset:18432
	ds_read_b128 v[164:167], v155 offset:19456
	ds_read_b128 v[168:171], v155 offset:20480
	ds_read_b128 v[172:175], v155 offset:21504
	ds_read_b128 v[176:179], v155 offset:22528
	ds_read_b128 v[180:183], v155 offset:23552
	global_load_lds_dwordx4 v[224:225], off
	s_add_i32 m0, s51, 0x2000
	s_add_u32 s64, s12, 0x80000
	v_lshl_add_u64 v[226:227], s[12:13], 0, v[4:5]
	s_addc_u32 s65, s13, 0
	s_add_i32 s51, s63, s38
	global_load_lds_dwordx4 v[226:227], off
	v_lshl_add_u64 v[228:229], s[64:65], 0, v[138:139]
	s_mov_b32 m0, s51
	v_lshl_add_u64 v[230:231], s[14:15], 0, v[136:137]
	global_load_lds_dwordx4 v[228:229], off
	v_lshl_add_u64 v[228:229], s[64:65], 0, v[4:5]
	s_add_i32 m0, s51, 0x2000
	s_nop 0
	global_load_lds_dwordx4 v[228:229], off
	v_lshl_add_u64 v[228:229], s[14:15], 0, v[140:141]
	s_mov_b32 m0, s39
	s_nop 0
	global_load_lds_dwordx4 v[228:229], off
	s_mov_b32 m0, s40
	s_nop 0
	global_load_lds_dwordx4 v[230:231], off
	s_waitcnt vmcnt(8)
	s_waitcnt lgkmcnt(0)
	s_barrier
	s_setprio 1
	s_waitcnt lgkmcnt(0)
	v_mfma_f32_16x16x32_bf16 v[68:71], v[184:187], v[150:153], v[68:71]
	v_mfma_f32_16x16x32_bf16 v[68:71], v[188:191], v[156:159], v[68:71]
	v_mfma_f32_16x16x32_bf16 v[64:67], v[192:195], v[150:153], v[64:67]
	v_mfma_f32_16x16x32_bf16 v[64:67], v[196:199], v[156:159], v[64:67]
	v_mfma_f32_16x16x32_bf16 v[60:63], v[208:211], v[150:153], v[60:63]
	v_mfma_f32_16x16x32_bf16 v[60:63], v[212:215], v[156:159], v[60:63]
	v_mfma_f32_16x16x32_bf16 v[56:59], v[216:219], v[150:153], v[56:59]
	v_mfma_f32_16x16x32_bf16 v[56:59], v[220:223], v[156:159], v[56:59]
	v_mfma_f32_16x16x32_bf16 v[52:55], v[184:187], v[160:163], v[52:55]
	v_mfma_f32_16x16x32_bf16 v[52:55], v[188:191], v[164:167], v[52:55]
	v_mfma_f32_16x16x32_bf16 v[48:51], v[192:195], v[160:163], v[48:51]
	v_mfma_f32_16x16x32_bf16 v[48:51], v[196:199], v[164:167], v[48:51]
	v_mfma_f32_16x16x32_bf16 v[44:47], v[208:211], v[160:163], v[44:47]
	v_mfma_f32_16x16x32_bf16 v[44:47], v[212:215], v[164:167], v[44:47]
	v_mfma_f32_16x16x32_bf16 v[40:43], v[216:219], v[160:163], v[40:43]
	v_mfma_f32_16x16x32_bf16 v[40:43], v[220:223], v[164:167], v[40:43]
	s_setprio 0
	s_setprio 1
	v_mfma_f32_16x16x32_bf16 v[36:39], v[184:187], v[168:171], v[36:39]
	v_mfma_f32_16x16x32_bf16 v[36:39], v[188:191], v[172:175], v[36:39]
	v_mfma_f32_16x16x32_bf16 v[32:35], v[192:195], v[168:171], v[32:35]
	v_mfma_f32_16x16x32_bf16 v[32:35], v[196:199], v[172:175], v[32:35]
	v_mfma_f32_16x16x32_bf16 v[28:31], v[208:211], v[168:171], v[28:31]
	v_mfma_f32_16x16x32_bf16 v[28:31], v[212:215], v[172:175], v[28:31]
	v_mfma_f32_16x16x32_bf16 v[24:27], v[216:219], v[168:171], v[24:27]
	v_mfma_f32_16x16x32_bf16 v[24:27], v[220:223], v[172:175], v[24:27]
	v_mfma_f32_16x16x32_bf16 v[20:23], v[184:187], v[176:179], v[20:23]
	v_mfma_f32_16x16x32_bf16 v[20:23], v[188:191], v[180:183], v[20:23]
	v_mfma_f32_16x16x32_bf16 v[16:19], v[192:195], v[176:179], v[16:19]
	v_mfma_f32_16x16x32_bf16 v[16:19], v[196:199], v[180:183], v[16:19]
	v_mfma_f32_16x16x32_bf16 v[12:15], v[208:211], v[176:179], v[12:15]
	v_mfma_f32_16x16x32_bf16 v[12:15], v[212:215], v[180:183], v[12:15]
	v_mfma_f32_16x16x32_bf16 v[8:11], v[216:219], v[176:179], v[8:11]
	v_mfma_f32_16x16x32_bf16 v[8:11], v[220:223], v[180:183], v[8:11]
	s_setprio 0
	s_barrier
	s_add_i32 s51, 0, 0x18000
	s_add_i32 s63, 0, 0x1c000
	s_add_u32 s14, s14, 0x80000
	v_add_u32_e32 v2, s51, v7
	s_addc_u32 s15, s15, 0
	s_mov_b32 m0, s41
	ds_read_b128 v[150:153], v155 offset:32768
	ds_read_b128 v[156:159], v155 offset:33792
	ds_read_b128 v[160:163], v155 offset:34816
	ds_read_b128 v[164:167], v155 offset:35840
	ds_read_b128 v[168:171], v155 offset:36864
	ds_read_b128 v[172:175], v155 offset:37888
	ds_read_b128 v[176:179], v155 offset:38912
	ds_read_b128 v[180:183], v155 offset:39936
	ds_read_b128 v[184:187], v2
	ds_read_b128 v[188:191], v2 offset:1024
	ds_read_b128 v[192:195], v2 offset:2048
	ds_read_b128 v[196:199], v2 offset:3072
	v_add_u32_e32 v2, s63, v7
	v_lshl_add_u64 v[232:233], s[14:15], 0, v[140:141]
	ds_read_b128 v[208:211], v2
	ds_read_b128 v[212:215], v2 offset:1024
	ds_read_b128 v[216:219], v2 offset:2048
	ds_read_b128 v[220:223], v2 offset:3072
	global_load_lds_dwordx4 v[232:233], off
	v_lshl_add_u64 v[232:233], s[14:15], 0, v[136:137]
	s_mov_b32 m0, s47
	s_nop 0
	global_load_lds_dwordx4 v[232:233], off
	s_waitcnt vmcnt(8)
	s_waitcnt lgkmcnt(0)
	s_barrier
	s_setprio 1
	s_waitcnt lgkmcnt(0)
	v_mfma_f32_16x16x32_bf16 v[132:135], v[184:187], v[150:153], v[132:135]
	v_mfma_f32_16x16x32_bf16 v[132:135], v[188:191], v[156:159], v[132:135]
	v_mfma_f32_16x16x32_bf16 v[128:131], v[192:195], v[150:153], v[128:131]
	v_mfma_f32_16x16x32_bf16 v[128:131], v[196:199], v[156:159], v[128:131]
	v_mfma_f32_16x16x32_bf16 v[124:127], v[208:211], v[150:153], v[124:127]
	v_mfma_f32_16x16x32_bf16 v[124:127], v[212:215], v[156:159], v[124:127]
	v_mfma_f32_16x16x32_bf16 v[120:123], v[216:219], v[150:153], v[120:123]
	v_mfma_f32_16x16x32_bf16 v[120:123], v[220:223], v[156:159], v[120:123]
	v_mfma_f32_16x16x32_bf16 v[116:119], v[184:187], v[160:163], v[116:119]
	v_mfma_f32_16x16x32_bf16 v[116:119], v[188:191], v[164:167], v[116:119]
	v_mfma_f32_16x16x32_bf16 v[112:115], v[192:195], v[160:163], v[112:115]
	v_mfma_f32_16x16x32_bf16 v[112:115], v[196:199], v[164:167], v[112:115]
	v_mfma_f32_16x16x32_bf16 v[108:111], v[208:211], v[160:163], v[108:111]
	v_mfma_f32_16x16x32_bf16 v[108:111], v[212:215], v[164:167], v[108:111]
	v_mfma_f32_16x16x32_bf16 v[104:107], v[216:219], v[160:163], v[104:107]
	v_mfma_f32_16x16x32_bf16 v[104:107], v[220:223], v[164:167], v[104:107]
	s_setprio 0
	s_setprio 1
	v_mfma_f32_16x16x32_bf16 v[100:103], v[184:187], v[168:171], v[100:103]
	v_mfma_f32_16x16x32_bf16 v[100:103], v[188:191], v[172:175], v[100:103]
	v_mfma_f32_16x16x32_bf16 v[96:99], v[192:195], v[168:171], v[96:99]
	v_mfma_f32_16x16x32_bf16 v[96:99], v[196:199], v[172:175], v[96:99]
	v_mfma_f32_16x16x32_bf16 v[92:95], v[208:211], v[168:171], v[92:95]
	v_mfma_f32_16x16x32_bf16 v[92:95], v[212:215], v[172:175], v[92:95]
	v_mfma_f32_16x16x32_bf16 v[88:91], v[216:219], v[168:171], v[88:91]
	v_mfma_f32_16x16x32_bf16 v[88:91], v[220:223], v[172:175], v[88:91]
	v_mfma_f32_16x16x32_bf16 v[84:87], v[184:187], v[176:179], v[84:87]
	v_mfma_f32_16x16x32_bf16 v[84:87], v[188:191], v[180:183], v[84:87]
	v_mfma_f32_16x16x32_bf16 v[80:83], v[192:195], v[176:179], v[80:83]
	v_mfma_f32_16x16x32_bf16 v[80:83], v[196:199], v[180:183], v[80:83]
	v_mfma_f32_16x16x32_bf16 v[76:79], v[208:211], v[176:179], v[76:79]
	v_mfma_f32_16x16x32_bf16 v[76:79], v[212:215], v[180:183], v[76:79]
	v_mfma_f32_16x16x32_bf16 v[72:75], v[216:219], v[176:179], v[72:75]
	v_mfma_f32_16x16x32_bf16 v[72:75], v[220:223], v[180:183], v[72:75]
	s_setprio 0
	s_barrier
	s_add_i32 s14, s51, s38
	v_lshl_add_u64 v[224:225], v[224:225], 0, s[0:1]
	s_mov_b32 m0, s14
	ds_read_b128 v[150:153], v155 offset:49152
	ds_read_b128 v[156:159], v155 offset:50176
	ds_read_b128 v[160:163], v155 offset:51200
	ds_read_b128 v[164:167], v155 offset:52224
	ds_read_b128 v[168:171], v155 offset:53248
	ds_read_b128 v[172:175], v155 offset:54272
	ds_read_b128 v[176:179], v155 offset:55296
	ds_read_b128 v[180:183], v155 offset:56320
	global_load_lds_dwordx4 v[224:225], off
	s_add_i32 m0, s14, 0x2000
	s_add_u32 s12, s12, 0x80080
	v_lshl_add_u64 v[224:225], v[226:227], 0, s[0:1]
	s_addc_u32 s13, s13, 0
	s_add_i32 s14, s63, s38
	global_load_lds_dwordx4 v[224:225], off
	v_lshl_add_u64 v[224:225], s[12:13], 0, v[138:139]
	s_mov_b32 m0, s14
	s_nop 0
	global_load_lds_dwordx4 v[224:225], off
	v_lshl_add_u64 v[224:225], s[12:13], 0, v[4:5]
	s_add_i32 m0, s14, 0x2000
	s_nop 0
	global_load_lds_dwordx4 v[224:225], off
	v_lshl_add_u64 v[224:225], v[228:229], 0, s[0:1]
	s_mov_b32 m0, s60
	s_nop 0
	global_load_lds_dwordx4 v[224:225], off
	v_lshl_add_u64 v[224:225], v[230:231], 0, s[0:1]
	s_mov_b32 m0, s61
	s_nop 0
	global_load_lds_dwordx4 v[224:225], off
	s_waitcnt vmcnt(8)
	s_waitcnt lgkmcnt(0)
	s_barrier
	s_setprio 1
	s_waitcnt lgkmcnt(0)
	v_mfma_f32_16x16x32_bf16 v[68:71], v[184:187], v[150:153], v[68:71]
	v_mfma_f32_16x16x32_bf16 v[68:71], v[188:191], v[156:159], v[68:71]
	v_mfma_f32_16x16x32_bf16 v[64:67], v[192:195], v[150:153], v[64:67]
	v_mfma_f32_16x16x32_bf16 v[64:67], v[196:199], v[156:159], v[64:67]
	v_mfma_f32_16x16x32_bf16 v[60:63], v[208:211], v[150:153], v[60:63]
	v_mfma_f32_16x16x32_bf16 v[60:63], v[212:215], v[156:159], v[60:63]
	v_mfma_f32_16x16x32_bf16 v[56:59], v[216:219], v[150:153], v[56:59]
	v_mfma_f32_16x16x32_bf16 v[56:59], v[220:223], v[156:159], v[56:59]
	v_mfma_f32_16x16x32_bf16 v[52:55], v[184:187], v[160:163], v[52:55]
	v_mfma_f32_16x16x32_bf16 v[52:55], v[188:191], v[164:167], v[52:55]
	v_mfma_f32_16x16x32_bf16 v[48:51], v[192:195], v[160:163], v[48:51]
	v_mfma_f32_16x16x32_bf16 v[48:51], v[196:199], v[164:167], v[48:51]
	v_mfma_f32_16x16x32_bf16 v[44:47], v[208:211], v[160:163], v[44:47]
	v_mfma_f32_16x16x32_bf16 v[44:47], v[212:215], v[164:167], v[44:47]
	v_mfma_f32_16x16x32_bf16 v[40:43], v[216:219], v[160:163], v[40:43]
	v_mfma_f32_16x16x32_bf16 v[40:43], v[220:223], v[164:167], v[40:43]
	s_setprio 0
	s_setprio 1
	v_mfma_f32_16x16x32_bf16 v[36:39], v[184:187], v[168:171], v[36:39]
	v_mfma_f32_16x16x32_bf16 v[36:39], v[188:191], v[172:175], v[36:39]
	v_mfma_f32_16x16x32_bf16 v[32:35], v[192:195], v[168:171], v[32:35]
	v_mfma_f32_16x16x32_bf16 v[32:35], v[196:199], v[172:175], v[32:35]
	v_mfma_f32_16x16x32_bf16 v[28:31], v[208:211], v[168:171], v[28:31]
	v_mfma_f32_16x16x32_bf16 v[28:31], v[212:215], v[172:175], v[28:31]
	v_mfma_f32_16x16x32_bf16 v[24:27], v[216:219], v[168:171], v[24:27]
	v_mfma_f32_16x16x32_bf16 v[24:27], v[220:223], v[172:175], v[24:27]
	v_mfma_f32_16x16x32_bf16 v[20:23], v[184:187], v[176:179], v[20:23]
	v_mfma_f32_16x16x32_bf16 v[20:23], v[188:191], v[180:183], v[20:23]
	v_mfma_f32_16x16x32_bf16 v[16:19], v[192:195], v[176:179], v[16:19]
	v_mfma_f32_16x16x32_bf16 v[16:19], v[196:199], v[180:183], v[16:19]
	v_mfma_f32_16x16x32_bf16 v[12:15], v[208:211], v[176:179], v[12:15]
	v_mfma_f32_16x16x32_bf16 v[12:15], v[212:215], v[180:183], v[12:15]
	v_mfma_f32_16x16x32_bf16 v[8:11], v[216:219], v[176:179], v[8:11]
	v_mfma_f32_16x16x32_bf16 v[8:11], v[220:223], v[180:183], v[8:11]
	s_setprio 0
	s_barrier
	s_add_i32 s50, s50, 2
	s_add_u32 s44, s44, 0x100
	s_addc_u32 s45, s45, 0
	s_add_u32 s33, s33, 0x100
	s_addc_u32 s43, s43, 0
	s_cmp_gt_u32 s50, 29
	s_cbranch_scc0 .LBB0_986
	s_and_b64 vcc, exec, s[10:11]
	s_cbranch_vccz .LBB0_1031
	s_barrier
	s_cmp_gt_i32 s35, 15
	s_mov_b64 s[12:13], -1
	s_cbranch_scc1 .LBB0_1032

.LBB0_1482:
	s_add_i32 s26, s12, 2
	s_cmp_eq_u32 s57, s12
	s_cselect_b32 s13, s43, s51
	s_cselect_b32 s12, s42, s50
	s_cselect_b32 s65, s45, s15
	s_cselect_b32 s64, s44, s14
	s_add_i32 s27, 0, 0x10000
	s_movk_i32 s66, 0xff80
	v_add_u32_e32 v121, s27, v7
	s_add_i32 s63, 0, 0x14000
	v_lshl_add_u64 v[178:179], s[50:51], 0, v[108:109]
	s_mov_b32 s67, -1
	ds_read_b128 v[110:113], v119
	ds_read_b128 v[114:117], v119 offset:1024
	ds_read_b128 v[122:125], v119 offset:2048
	ds_read_b128 v[126:129], v119 offset:3072
	ds_read_b128 v[130:133], v119 offset:4096
	ds_read_b128 v[134:137], v119 offset:5120
	ds_read_b128 v[138:141], v119 offset:6144
	ds_read_b128 v[142:145], v119 offset:7168
	ds_read_b128 v[146:149], v121
	ds_read_b128 v[150:153], v121 offset:1024
	ds_read_b128 v[154:157], v121 offset:2048
	ds_read_b128 v[158:161], v121 offset:3072
	v_add_u32_e32 v121, s63, v7
	v_lshl_add_u64 v[178:179], v[178:179], 0, s[66:67]
	s_add_i32 m0, s39, 0xc000
	ds_read_b128 v[162:165], v121
	ds_read_b128 v[166:169], v121 offset:1024
	ds_read_b128 v[170:173], v121 offset:2048
	ds_read_b128 v[174:177], v121 offset:3072
	global_load_lds_dwordx4 v[178:179], off
	s_waitcnt vmcnt(7)
	s_waitcnt lgkmcnt(0)
	s_barrier
	s_setprio 1
	s_waitcnt lgkmcnt(0)
	v_mfma_f32_16x16x32_bf16 v[100:103], v[146:149], v[110:113], v[100:103]
	v_mfma_f32_16x16x32_bf16 v[100:103], v[150:153], v[114:117], v[100:103]
	v_mfma_f32_16x16x32_bf16 v[96:99], v[154:157], v[110:113], v[96:99]
	v_mfma_f32_16x16x32_bf16 v[96:99], v[158:161], v[114:117], v[96:99]
	v_mfma_f32_16x16x32_bf16 v[88:91], v[162:165], v[110:113], v[88:91]
	v_mfma_f32_16x16x32_bf16 v[88:91], v[166:169], v[114:117], v[88:91]
	v_mfma_f32_16x16x32_bf16 v[84:87], v[170:173], v[110:113], v[84:87]
	v_mfma_f32_16x16x32_bf16 v[84:87], v[174:177], v[114:117], v[84:87]
	v_mfma_f32_16x16x32_bf16 v[92:95], v[146:149], v[122:125], v[92:95]
	v_mfma_f32_16x16x32_bf16 v[92:95], v[150:153], v[126:129], v[92:95]
	v_mfma_f32_16x16x32_bf16 v[80:83], v[154:157], v[122:125], v[80:83]
	v_mfma_f32_16x16x32_bf16 v[80:83], v[158:161], v[126:129], v[80:83]
	v_mfma_f32_16x16x32_bf16 v[76:79], v[162:165], v[122:125], v[76:79]
	v_mfma_f32_16x16x32_bf16 v[76:79], v[166:169], v[126:129], v[76:79]
	v_mfma_f32_16x16x32_bf16 v[68:71], v[170:173], v[122:125], v[68:71]
	v_mfma_f32_16x16x32_bf16 v[68:71], v[174:177], v[126:129], v[68:71]
	s_setprio 0
	s_setprio 1
	v_mfma_f32_16x16x32_bf16 v[72:75], v[146:149], v[130:133], v[72:75]
	v_mfma_f32_16x16x32_bf16 v[72:75], v[150:153], v[134:137], v[72:75]
	v_mfma_f32_16x16x32_bf16 v[64:67], v[154:157], v[130:133], v[64:67]
	v_mfma_f32_16x16x32_bf16 v[64:67], v[158:161], v[134:137], v[64:67]
	v_mfma_f32_16x16x32_bf16 v[60:63], v[162:165], v[130:133], v[60:63]
	v_mfma_f32_16x16x32_bf16 v[60:63], v[166:169], v[134:137], v[60:63]
	v_mfma_f32_16x16x32_bf16 v[52:55], v[170:173], v[130:133], v[52:55]
	v_mfma_f32_16x16x32_bf16 v[52:55], v[174:177], v[134:137], v[52:55]
	v_mfma_f32_16x16x32_bf16 v[56:59], v[146:149], v[138:141], v[56:59]
	v_mfma_f32_16x16x32_bf16 v[56:59], v[150:153], v[142:145], v[56:59]
	v_mfma_f32_16x16x32_bf16 v[48:51], v[154:157], v[138:141], v[48:51]
	v_mfma_f32_16x16x32_bf16 v[48:51], v[158:161], v[142:145], v[48:51]
	v_mfma_f32_16x16x32_bf16 v[44:47], v[162:165], v[138:141], v[44:47]
	v_mfma_f32_16x16x32_bf16 v[44:47], v[166:169], v[142:145], v[44:47]
	v_mfma_f32_16x16x32_bf16 v[40:43], v[170:173], v[138:141], v[40:43]
	v_mfma_f32_16x16x32_bf16 v[40:43], v[174:177], v[142:145], v[40:43]
	s_setprio 0
	s_barrier
	s_add_i32 s27, s27, s22
	v_lshl_add_u64 v[178:179], s[64:65], 0, v[2:3]
	s_mov_b32 m0, s27
	ds_read_b128 v[110:113], v120 offset:16384
	ds_read_b128 v[114:117], v120 offset:17408
	ds_read_b128 v[122:125], v120 offset:18432
	ds_read_b128 v[126:129], v120 offset:19456
	global_load_lds_dwordx4 v[178:179], off
	s_add_i32 m0, s27, 0x2000
	v_lshl_add_u64 v[180:181], s[64:65], 0, v[4:5]
	s_add_u32 s64, s64, s90
	s_addc_u32 s65, s65, 0
	s_add_i32 s27, s63, s22
	global_load_lds_dwordx4 v[180:181], off
	v_lshl_add_u64 v[182:183], s[64:65], 0, v[2:3]
	s_mov_b32 m0, s27
	v_lshl_add_u64 v[184:185], s[64:65], 0, v[4:5]
	global_load_lds_dwordx4 v[182:183], off
	s_add_i32 m0, s27, 0x2000
	v_lshl_add_u64 v[186:187], s[12:13], 0, v[106:107]
	global_load_lds_dwordx4 v[184:185], off
	s_mov_b32 m0, s39
	v_lshl_add_u64 v[188:189], s[12:13], 0, v[104:105]
	global_load_lds_dwordx4 v[186:187], off
	s_mov_b32 m0, s40
	s_nop 0
	global_load_lds_dwordx4 v[188:189], off
	s_waitcnt vmcnt(7)
	s_waitcnt lgkmcnt(0)
	s_barrier
	s_setprio 1
	s_waitcnt lgkmcnt(0)
	v_mfma_f32_16x16x32_bf16 v[36:39], v[146:149], v[110:113], v[36:39]
	v_mfma_f32_16x16x32_bf16 v[36:39], v[150:153], v[114:117], v[36:39]
	v_mfma_f32_16x16x32_bf16 v[32:35], v[154:157], v[110:113], v[32:35]
	v_mfma_f32_16x16x32_bf16 v[32:35], v[158:161], v[114:117], v[32:35]
	v_mfma_f32_16x16x32_bf16 v[28:31], v[162:165], v[110:113], v[28:31]
	v_mfma_f32_16x16x32_bf16 v[28:31], v[166:169], v[114:117], v[28:31]
	v_mfma_f32_16x16x32_bf16 v[24:27], v[170:173], v[110:113], v[24:27]
	v_mfma_f32_16x16x32_bf16 v[24:27], v[174:177], v[114:117], v[24:27]
	s_setprio 0
	s_setprio 1
	v_mfma_f32_16x16x32_bf16 v[20:23], v[146:149], v[122:125], v[20:23]
	v_mfma_f32_16x16x32_bf16 v[20:23], v[150:153], v[126:129], v[20:23]
	v_mfma_f32_16x16x32_bf16 v[16:19], v[154:157], v[122:125], v[16:19]
	v_mfma_f32_16x16x32_bf16 v[16:19], v[158:161], v[126:129], v[16:19]
	v_mfma_f32_16x16x32_bf16 v[12:15], v[162:165], v[122:125], v[12:15]
	v_mfma_f32_16x16x32_bf16 v[12:15], v[166:169], v[126:129], v[12:15]
	v_mfma_f32_16x16x32_bf16 v[8:11], v[170:173], v[122:125], v[8:11]
	v_mfma_f32_16x16x32_bf16 v[8:11], v[174:177], v[126:129], v[8:11]
	s_setprio 0
	s_barrier
	s_add_i32 s27, 0, 0x18000
	s_add_i32 s63, 0, 0x1c000
	s_add_u32 s12, s12, s90
	v_add_u32_e32 v121, s27, v7
	s_addc_u32 s13, s13, 0
	ds_read_b128 v[110:113], v119 offset:32768
	ds_read_b128 v[114:117], v119 offset:33792
	ds_read_b128 v[122:125], v119 offset:34816
	ds_read_b128 v[126:129], v119 offset:35840
	ds_read_b128 v[130:133], v119 offset:36864
	ds_read_b128 v[134:137], v119 offset:37888
	ds_read_b128 v[138:141], v119 offset:38912
	ds_read_b128 v[142:145], v119 offset:39936
	ds_read_b128 v[146:149], v121
	ds_read_b128 v[150:153], v121 offset:1024
	ds_read_b128 v[154:157], v121 offset:2048
	ds_read_b128 v[158:161], v121 offset:3072
	v_add_u32_e32 v121, s63, v7
	v_lshl_add_u64 v[190:191], s[12:13], 0, v[106:107]
	s_mov_b32 m0, s41
	ds_read_b128 v[162:165], v121
	ds_read_b128 v[166:169], v121 offset:1024
	ds_read_b128 v[170:173], v121 offset:2048
	ds_read_b128 v[174:177], v121 offset:3072
	global_load_lds_dwordx4 v[190:191], off
	s_waitcnt vmcnt(7)
	s_waitcnt lgkmcnt(0)
	s_barrier
	s_setprio 1
	s_waitcnt lgkmcnt(0)
	v_mfma_f32_16x16x32_bf16 v[100:103], v[146:149], v[110:113], v[100:103]
	v_mfma_f32_16x16x32_bf16 v[100:103], v[150:153], v[114:117], v[100:103]
	v_mfma_f32_16x16x32_bf16 v[96:99], v[154:157], v[110:113], v[96:99]
	v_mfma_f32_16x16x32_bf16 v[96:99], v[158:161], v[114:117], v[96:99]
	v_mfma_f32_16x16x32_bf16 v[88:91], v[162:165], v[110:113], v[88:91]
	v_mfma_f32_16x16x32_bf16 v[88:91], v[166:169], v[114:117], v[88:91]
	v_mfma_f32_16x16x32_bf16 v[84:87], v[170:173], v[110:113], v[84:87]
	v_mfma_f32_16x16x32_bf16 v[84:87], v[174:177], v[114:117], v[84:87]
	v_mfma_f32_16x16x32_bf16 v[92:95], v[146:149], v[122:125], v[92:95]
	v_mfma_f32_16x16x32_bf16 v[92:95], v[150:153], v[126:129], v[92:95]
	v_mfma_f32_16x16x32_bf16 v[80:83], v[154:157], v[122:125], v[80:83]
	v_mfma_f32_16x16x32_bf16 v[80:83], v[158:161], v[126:129], v[80:83]
	v_mfma_f32_16x16x32_bf16 v[76:79], v[162:165], v[122:125], v[76:79]
	v_mfma_f32_16x16x32_bf16 v[76:79], v[166:169], v[126:129], v[76:79]
	v_mfma_f32_16x16x32_bf16 v[68:71], v[170:173], v[122:125], v[68:71]
	v_mfma_f32_16x16x32_bf16 v[68:71], v[174:177], v[126:129], v[68:71]
	s_setprio 0
	s_setprio 1
	v_mfma_f32_16x16x32_bf16 v[72:75], v[146:149], v[130:133], v[72:75]
	v_mfma_f32_16x16x32_bf16 v[72:75], v[150:153], v[134:137], v[72:75]
	v_mfma_f32_16x16x32_bf16 v[64:67], v[154:157], v[130:133], v[64:67]
	v_mfma_f32_16x16x32_bf16 v[64:67], v[158:161], v[134:137], v[64:67]
	v_mfma_f32_16x16x32_bf16 v[60:63], v[162:165], v[130:133], v[60:63]
	v_mfma_f32_16x16x32_bf16 v[60:63], v[166:169], v[134:137], v[60:63]
	v_mfma_f32_16x16x32_bf16 v[52:55], v[170:173], v[130:133], v[52:55]
	v_mfma_f32_16x16x32_bf16 v[52:55], v[174:177], v[134:137], v[52:55]
	v_mfma_f32_16x16x32_bf16 v[56:59], v[146:149], v[138:141], v[56:59]
	v_mfma_f32_16x16x32_bf16 v[56:59], v[150:153], v[142:145], v[56:59]
	v_mfma_f32_16x16x32_bf16 v[48:51], v[154:157], v[138:141], v[48:51]
	v_mfma_f32_16x16x32_bf16 v[48:51], v[158:161], v[142:145], v[48:51]
	v_mfma_f32_16x16x32_bf16 v[44:47], v[162:165], v[138:141], v[44:47]
	v_mfma_f32_16x16x32_bf16 v[44:47], v[166:169], v[142:145], v[44:47]
	v_mfma_f32_16x16x32_bf16 v[40:43], v[170:173], v[138:141], v[40:43]
	v_mfma_f32_16x16x32_bf16 v[40:43], v[174:177], v[142:145], v[40:43]
	s_setprio 0
	s_barrier
	s_add_i32 s12, s27, s22
	v_lshl_add_u64 v[130:131], v[178:179], 0, s[0:1]
	s_mov_b32 m0, s12
	ds_read_b128 v[110:113], v120 offset:49152
	ds_read_b128 v[114:117], v120 offset:50176
	ds_read_b128 v[122:125], v120 offset:51200
	ds_read_b128 v[126:129], v120 offset:52224
	global_load_lds_dwordx4 v[130:131], off
	v_lshl_add_u64 v[130:131], v[180:181], 0, s[0:1]
	s_add_i32 m0, s12, 0x2000
	s_add_i32 s12, s63, s22
	global_load_lds_dwordx4 v[130:131], off
	v_lshl_add_u64 v[130:131], v[182:183], 0, s[0:1]
	s_mov_b32 m0, s12
	s_nop 0
	global_load_lds_dwordx4 v[130:131], off
	v_lshl_add_u64 v[130:131], v[184:185], 0, s[0:1]
	s_add_i32 m0, s12, 0x2000
	s_nop 0
	global_load_lds_dwordx4 v[130:131], off
	v_lshl_add_u64 v[130:131], v[186:187], 0, s[0:1]
	s_mov_b32 m0, s53
	s_nop 0
	global_load_lds_dwordx4 v[130:131], off
	v_lshl_add_u64 v[130:131], v[188:189], 0, s[0:1]
	s_mov_b32 m0, s54
	s_nop 0
	global_load_lds_dwordx4 v[130:131], off
	s_waitcnt vmcnt(7)
	s_waitcnt lgkmcnt(0)
	s_barrier
	s_setprio 1
	s_waitcnt lgkmcnt(0)
	v_mfma_f32_16x16x32_bf16 v[36:39], v[146:149], v[110:113], v[36:39]
	v_mfma_f32_16x16x32_bf16 v[36:39], v[150:153], v[114:117], v[36:39]
	v_mfma_f32_16x16x32_bf16 v[32:35], v[154:157], v[110:113], v[32:35]
	v_mfma_f32_16x16x32_bf16 v[32:35], v[158:161], v[114:117], v[32:35]
	v_mfma_f32_16x16x32_bf16 v[28:31], v[162:165], v[110:113], v[28:31]
	v_mfma_f32_16x16x32_bf16 v[28:31], v[166:169], v[114:117], v[28:31]
	v_mfma_f32_16x16x32_bf16 v[24:27], v[170:173], v[110:113], v[24:27]
	v_mfma_f32_16x16x32_bf16 v[24:27], v[174:177], v[114:117], v[24:27]
	s_setprio 0
	s_setprio 1
	v_mfma_f32_16x16x32_bf16 v[20:23], v[146:149], v[122:125], v[20:23]
	v_mfma_f32_16x16x32_bf16 v[20:23], v[150:153], v[126:129], v[20:23]
	v_mfma_f32_16x16x32_bf16 v[16:19], v[154:157], v[122:125], v[16:19]
	v_mfma_f32_16x16x32_bf16 v[16:19], v[158:161], v[126:129], v[16:19]
	v_mfma_f32_16x16x32_bf16 v[12:15], v[162:165], v[122:125], v[12:15]
	v_mfma_f32_16x16x32_bf16 v[12:15], v[166:169], v[126:129], v[12:15]
	v_mfma_f32_16x16x32_bf16 v[8:11], v[170:173], v[122:125], v[8:11]
	v_mfma_f32_16x16x32_bf16 v[8:11], v[174:177], v[126:129], v[8:11]
	s_setprio 0
	s_barrier
	s_add_u32 s50, s50, 0x100
	s_addc_u32 s51, s51, 0
	s_add_u32 s14, s14, 0x100
	s_addc_u32 s15, s15, 0
	s_cmp_ge_u32 s26, s55
	s_mov_b32 s12, s26
	s_cbranch_scc0 .LBB0_1482
	s_and_b64 vcc, exec, s[36:37]
	s_cbranch_vccz .LBB0_1485
	s_barrier
